# rmsnorm row reductions via permlane swaps + DPP instead of ds_bpermute round trips; flash mask-index sink with MFMA-result read reorder
# speedup vs baseline: 1.1560x; 1.0092x over previous
; __device__ __forceinline__ u32x2 pack4(f32x4 v) { u32x2 r; r.x = cvt_pk_bf16(v[0], v[1]); r.y = cvt_pk_bf16(v[2], v[3]); return r; }
; __device__ __forceinline__ void rmsnorm_phase(const float* x, const float* g, bf16_t* outb, float* outf) {
;     ...
;     for (int row = gw; row < T; row += nw) {
;         const float* xr = x + (size_t)row * D;
;         f32x4 v[4];
;         float ss = 0.f;
; #pragma unroll
;         for (int i = 0; i < 4; ++i) { v[i] = __builtin_nontemporal_load((const f32x4*)(xr + (lane + i * 64) * 4)); ss += v[i][0] * v[i][0] + v[i][1] * v[i][1] + v[i][2] * v[i][2] + v[i][3] * v[i][3]; }
; #pragma unroll
;         for (int o = 32; o >= 1; o >>= 1) ss += __shfl_xor(ss, o);
;         const float r = rsqrtf(ss * (1.0f / D) + EPS);
; #pragma unroll
;         for (int i = 0; i < 4; ++i) {
;             const f32x4 y = v[i] * r * gv[i];
;             if (outb) *(u32x2*)(outb + (size_t)row * D + (lane + i * 64) * 4) = pack4(y);
;             else __builtin_nontemporal_store(y, (f32x4*)(outf + (size_t)row * D + (lane + i * 64) * 4));
;         }
;     }
.LBB0_100:
	global_load_dwordx4 v[28:31], v[18:19], off offset:-3072 nt
	global_load_dwordx4 v[32:35], v[18:19], off offset:-2048 nt
	global_load_dwordx4 v[36:39], v[18:19], off offset:-1024 nt
	global_load_dwordx4 v[40:43], v[18:19], off nt
	v_add_u32_e32 v27, s10, v27
	v_cmp_lt_i32_e32 vcc, s9, v27
	s_or_b64 s[6:7], vcc, s[6:7]
	v_lshl_add_u64 v[18:19], v[18:19], 0, s[4:5]
	s_waitcnt vmcnt(3)
	v_mov_b32_e32 v46, v29
	s_waitcnt vmcnt(2)
	v_mov_b32_e32 v47, v33
	v_mov_b32_e32 v44, v28
	v_mov_b32_e32 v45, v32
	s_waitcnt vmcnt(1)
	v_mov_b32_e32 v54, v37
	s_waitcnt vmcnt(0)
	v_mov_b32_e32 v55, v41
	v_pk_mul_f32 v[46:47], v[46:47], v[46:47]
	v_mov_b32_e32 v48, v30
	v_mov_b32_e32 v49, v34
	v_mov_b32_e32 v52, v36
	v_mov_b32_e32 v53, v40
	v_pk_mul_f32 v[54:55], v[54:55], v[54:55]
	v_pk_fma_f32 v[44:45], v[44:45], v[44:45], v[46:47]
	v_mov_b32_e32 v50, v31
	v_mov_b32_e32 v51, v35
	v_mov_b32_e32 v56, v38
	v_mov_b32_e32 v57, v42
	v_pk_fma_f32 v[46:47], v[52:53], v[52:53], v[54:55]
	v_pk_fma_f32 v[44:45], v[48:49], v[48:49], v[44:45]
	v_mov_b32_e32 v58, v39
	v_mov_b32_e32 v59, v43
	v_pk_fma_f32 v[46:47], v[56:57], v[56:57], v[46:47]
	v_pk_fma_f32 v[44:45], v[50:51], v[50:51], v[44:45]
	v_pk_fma_f32 v[46:47], v[58:59], v[58:59], v[46:47]
	v_add_f32_e32 v44, v44, v45
	v_add_f32_e32 v44, v44, v46
	v_add_f32_e32 v44, v44, v47
	v_mov_b32_e32 v45, v44
	s_nop 1
	v_permlane32_swap_b32_e32 v44, v45
	v_add_f32_e32 v44, v44, v45
	v_mov_b32_e32 v45, v44
	s_nop 1
	v_permlane16_swap_b32_e32 v44, v45
	v_add_f32_e32 v44, v44, v45
	s_nop 1
	v_add_f32_dpp v44, v44, v44 row_ror:8 row_mask:0xf bank_mask:0xf
	s_nop 1
	v_add_f32_dpp v44, v44, v44 row_ror:4 row_mask:0xf bank_mask:0xf
	s_nop 1
	v_add_f32_dpp v44, v44, v44 quad_perm:[2,3,0,1] row_mask:0xf bank_mask:0xf
	s_nop 1
	v_add_f32_dpp v44, v44, v44 quad_perm:[1,0,3,2] row_mask:0xf bank_mask:0xf
	v_fmamk_f32 v44, v44, 0x3a800000, v26
	v_mul_f32_e32 v45, 0x4b800000, v44
	v_cmp_gt_f32_e32 vcc, s8, v44
	s_nop 1
	v_cndmask_b32_e32 v44, v44, v45, vcc
	v_rsq_f32_e32 v44, v44
	s_nop 0
	v_mul_f32_e32 v45, 0x45800000, v44
	v_cndmask_b32_e32 v44, v44, v45, vcc
	v_pk_mul_f32 v[28:29], v[28:29], v[44:45] op_sel_hi:[1,0]
	v_pk_mul_f32 v[30:31], v[30:31], v[44:45] op_sel_hi:[1,0]
	v_pk_mul_f32 v[32:33], v[32:33], v[44:45] op_sel_hi:[1,0]
	v_pk_mul_f32 v[34:35], v[34:35], v[44:45] op_sel_hi:[1,0]
	v_pk_mul_f32 v[36:37], v[36:37], v[44:45] op_sel_hi:[1,0]
	v_pk_mul_f32 v[38:39], v[38:39], v[44:45] op_sel_hi:[1,0]
	v_pk_mul_f32 v[40:41], v[40:41], v[44:45] op_sel_hi:[1,0]
	v_pk_mul_f32 v[42:43], v[42:43], v[44:45] op_sel_hi:[1,0]
	v_pk_mul_f32 v[30:31], v[2:3], v[30:31]
	v_pk_mul_f32 v[28:29], v[0:1], v[28:29]
	v_pk_mul_f32 v[34:35], v[6:7], v[34:35]
	v_pk_mul_f32 v[32:33], v[4:5], v[32:33]
	v_pk_mul_f32 v[38:39], v[10:11], v[38:39]
	v_pk_mul_f32 v[36:37], v[8:9], v[36:37]
	v_pk_mul_f32 v[42:43], v[14:15], v[42:43]
	v_pk_mul_f32 v[40:41], v[12:13], v[40:41]
	v_cvt_pk_bf16_f32 v28, v28, v29
	v_cvt_pk_bf16_f32 v29, v30, v31
	v_cvt_pk_bf16_f32 v30, v32, v33
	v_cvt_pk_bf16_f32 v31, v34, v35
	v_cvt_pk_bf16_f32 v32, v36, v37
	v_cvt_pk_bf16_f32 v33, v38, v39
	v_cvt_pk_bf16_f32 v34, v40, v41
	v_cvt_pk_bf16_f32 v35, v42, v43
	global_store_dwordx2 v[16:17], v[28:29], off
	global_store_dwordx2 v[16:17], v[30:31], off offset:512
	global_store_dwordx2 v[16:17], v[32:33], off offset:1024
	global_store_dwordx2 v[16:17], v[34:35], off offset:1536
	v_lshl_add_u64 v[16:17], v[16:17], 0, s[2:3]
	s_andn2_b64 exec, exec, s[6:7]
	s_cbranch_execnz .LBB0_100

; __device__ __forceinline__ f32x4 mfma16(bf16x8 a, bf16x8 b, f32x4 c) { return __builtin_amdgcn_mfma_f32_16x16x32_bf16(a, b, c, 0, 0, 0); }
; template <class Epi>
; __device__ __forceinline__ void gemm_tile(const bf16_t* __restrict__ A, const bf16_t* __restrict__ Bt, int K, int row0, int col0, const Epi& epi, char* smem,
;                                           bool prefetched, bool nvalid, int nrow0, int ncol0) {
;     ...
;     for (int kt = 0; kt < nk; ++kt) {
;         const int cur = kt & 1;
;         if (kt + 1 < nk) GLDS_STAGE(cur ^ 1, pA, pB, kt + 1);
;         const char* cb = smem + cur * 2 * TILE_B;
; #pragma unroll
;         for (int ks = 0; ks < 2; ++ks) {
;             bf16x8 a[4], b[4];
; #pragma unroll
;             for (int m = 0; m < 4; ++m) a[m] = *(const bf16x8*)(cb + offA[m][ks]);
; #pragma unroll
;             for (int n = 0; n < 4; ++n) b[n] = *(const bf16x8*)(cb + offB[n][ks]);
; #pragma unroll
;             for (int m = 0; m < 4; ++m)
; #pragma unroll
;                 for (int n = 0; n < 4; ++n) acc[m][n] = mfma16(b[n], a[m], acc[m][n]);
;         }
;         asm volatile("s_waitcnt vmcnt(0)" ::: "memory");
;         __syncthreads();
.LBB0_154:
	v_readfirstlane_b32 s98, v64
	v_readfirstlane_b32 s99, v65
	v_readfirstlane_b32 s10, v66
	v_readfirstlane_b32 s100, v72
	v_readfirstlane_b32 s101, v73
	v_readfirstlane_b32 s13, v149
	s_nop 3
	s_sub_u32 s14, s10, s98
	s_and_b32 s98, s98, 0xffffff80
	s_and_b32 s100, s100, 0xffffff80
	s_nop 1
	v_subrev_u32_e32 v254, s98, v64
	v_subrev_u32_e32 v255, s100, v72
	s_add_i32 s12, s13, 0x8000
	s_mov_b32 m0, s12
	s_nop 0
	global_load_lds_dwordx4 v254, s[98:99]
	s_add_i32 m0, s12, 0x1000
	s_add_u32 s10, s98, s14
	s_addc_u32 s11, s99, 0
	global_load_lds_dwordx4 v254, s[10:11]
	s_add_i32 m0, s12, 0x2000
	s_add_u32 s10, s10, s14
	s_addc_u32 s11, s11, 0
	global_load_lds_dwordx4 v254, s[10:11]
	s_add_i32 m0, s12, 0x3000
	s_add_u32 s10, s10, s14
	s_addc_u32 s11, s11, 0
	global_load_lds_dwordx4 v254, s[10:11]
	s_add_u32 s98, s98, 0x80
	s_addc_u32 s99, s99, 0
	ds_read_b128 v[182:185], v139
	ds_read_b128 v[64:67], v142 offset:16384
	ds_read_b128 v[68:71], v142 offset:16896
	ds_read_b128 v[72:75], v142 offset:20480
	ds_read_b128 v[76:79], v142 offset:20992
	ds_read_b128 v[186:189], v139 offset:2048
	ds_read_b128 v[246:249], v139 offset:4096
	ds_read_b128 v[250:253], v139 offset:6144
.Lgk_loop_154:
	s_and_b32 s8, s5, 0x8000
	s_xor_b32 s9, s8, 0x8000
	v_or_b32_e32 v173, s8, v141
	v_add_u32_e32 v190, s8, v140
	s_add_i32 m0, s12, 0x4000
	s_nop 0
	s_waitcnt lgkmcnt(6)
	v_mfma_f32_16x16x32_bf16 v[0:3], v[64:67], v[182:185], v[0:3]
	global_load_lds_dwordx4 v255, s[100:101]
	ds_read_b128 v[80:83], v173 offset:16384
	s_waitcnt lgkmcnt(6)
	v_mfma_f32_16x16x32_bf16 v[4:7], v[68:71], v[182:185], v[4:7]
	ds_read_b128 v[128:131], v173 offset:16896
	s_add_i32 m0, s12, 0x5000
	s_add_u32 s10, s100, s14
	s_addc_u32 s11, s101, 0
	s_waitcnt lgkmcnt(6)
	v_mfma_f32_16x16x32_bf16 v[8:11], v[72:75], v[182:185], v[8:11]
	global_load_lds_dwordx4 v255, s[10:11]
	ds_read_b128 v[174:177], v173 offset:20480
	s_waitcnt lgkmcnt(6)
	v_mfma_f32_16x16x32_bf16 v[12:15], v[76:79], v[182:185], v[12:15]
	ds_read_b128 v[178:181], v173 offset:20992
	ds_read_b128 v[182:185], v190
	s_add_i32 m0, s12, 0x6000
	s_add_u32 s10, s10, s14
	s_addc_u32 s11, s11, 0
	s_waitcnt lgkmcnt(7)
	v_mfma_f32_16x16x32_bf16 v[16:19], v[64:67], v[186:189], v[16:19]
	global_load_lds_dwordx4 v255, s[10:11]
	v_mfma_f32_16x16x32_bf16 v[20:23], v[68:71], v[186:189], v[20:23]
	s_add_i32 m0, s12, 0x7000
	s_add_u32 s10, s10, s14
	s_addc_u32 s11, s11, 0
	v_mfma_f32_16x16x32_bf16 v[24:27], v[72:75], v[186:189], v[24:27]
	global_load_lds_dwordx4 v255, s[10:11]
	s_add_u32 s100, s100, 0x80
	s_addc_u32 s101, s101, 0
	v_mfma_f32_16x16x32_bf16 v[28:31], v[76:79], v[186:189], v[28:31]
	ds_read_b128 v[186:189], v190 offset:2048
	s_waitcnt lgkmcnt(7)
	v_mfma_f32_16x16x32_bf16 v[32:35], v[64:67], v[246:249], v[32:35]
	v_mfma_f32_16x16x32_bf16 v[36:39], v[68:71], v[246:249], v[36:39]
	v_mfma_f32_16x16x32_bf16 v[40:43], v[72:75], v[246:249], v[40:43]
	v_mfma_f32_16x16x32_bf16 v[44:47], v[76:79], v[246:249], v[44:47]
	ds_read_b128 v[246:249], v190 offset:4096
	s_waitcnt lgkmcnt(7)
	v_mfma_f32_16x16x32_bf16 v[48:51], v[64:67], v[250:253], v[48:51]
	v_mfma_f32_16x16x32_bf16 v[52:55], v[68:71], v[250:253], v[52:55]
	v_mfma_f32_16x16x32_bf16 v[56:59], v[72:75], v[250:253], v[56:59]
	v_mfma_f32_16x16x32_bf16 v[60:63], v[76:79], v[250:253], v[60:63]
	ds_read_b128 v[250:253], v190 offset:6144
	s_waitcnt lgkmcnt(3)
	v_mfma_f32_16x16x32_bf16 v[0:3], v[80:83], v[182:185], v[0:3]
	v_mfma_f32_16x16x32_bf16 v[4:7], v[128:131], v[182:185], v[4:7]
	v_mfma_f32_16x16x32_bf16 v[8:11], v[174:177], v[182:185], v[8:11]
	v_mfma_f32_16x16x32_bf16 v[12:15], v[178:181], v[182:185], v[12:15]
	s_waitcnt lgkmcnt(2)
	v_mfma_f32_16x16x32_bf16 v[16:19], v[80:83], v[186:189], v[16:19]
	v_mfma_f32_16x16x32_bf16 v[20:23], v[128:131], v[186:189], v[20:23]
	v_mfma_f32_16x16x32_bf16 v[24:27], v[174:177], v[186:189], v[24:27]
	v_mfma_f32_16x16x32_bf16 v[28:31], v[178:181], v[186:189], v[28:31]
	s_waitcnt vmcnt(0)
	s_waitcnt lgkmcnt(0)
	s_barrier
	s_add_i32 s5, s5, 0x8000
	s_cmp_eq_u32 s5, 0x78000
	s_cbranch_scc1 .Lgk_tail_154
	v_or_b32_e32 v173, s9, v142
	v_add_u32_e32 v190, s9, v139
	s_add_i32 s12, s8, s13
	ds_read_b128 v[182:185], v190
	ds_read_b128 v[64:67], v173 offset:16384
	s_mov_b32 m0, s12
	s_nop 0
	v_mfma_f32_16x16x32_bf16 v[32:35], v[80:83], v[246:249], v[32:35]
	global_load_lds_dwordx4 v254, s[98:99]
	ds_read_b128 v[68:71], v173 offset:16896
	v_mfma_f32_16x16x32_bf16 v[36:39], v[128:131], v[246:249], v[36:39]
	ds_read_b128 v[72:75], v173 offset:20480
	s_add_i32 m0, s12, 0x1000
	s_add_u32 s10, s98, s14
	s_addc_u32 s11, s99, 0
	v_mfma_f32_16x16x32_bf16 v[40:43], v[174:177], v[246:249], v[40:43]
	global_load_lds_dwordx4 v254, s[10:11]
	ds_read_b128 v[76:79], v173 offset:20992
	v_mfma_f32_16x16x32_bf16 v[44:47], v[178:181], v[246:249], v[44:47]
	ds_read_b128 v[186:189], v190 offset:2048
	ds_read_b128 v[246:249], v190 offset:4096
	s_add_i32 m0, s12, 0x2000
	s_add_u32 s10, s10, s14
	s_addc_u32 s11, s11, 0
	v_mfma_f32_16x16x32_bf16 v[48:51], v[80:83], v[250:253], v[48:51]
	global_load_lds_dwordx4 v254, s[10:11]
	v_mfma_f32_16x16x32_bf16 v[52:55], v[128:131], v[250:253], v[52:55]
	s_add_i32 m0, s12, 0x3000
	s_add_u32 s10, s10, s14
	s_addc_u32 s11, s11, 0
	v_mfma_f32_16x16x32_bf16 v[56:59], v[174:177], v[250:253], v[56:59]
	global_load_lds_dwordx4 v254, s[10:11]
	s_add_u32 s98, s98, 0x80
	s_addc_u32 s99, s99, 0
	v_mfma_f32_16x16x32_bf16 v[60:63], v[178:181], v[250:253], v[60:63]
	ds_read_b128 v[250:253], v190 offset:6144
	s_branch .Lgk_loop_154

; __device__ __forceinline__ f32x4 mfma16(bf16x8 a, bf16x8 b, f32x4 c) { return __builtin_amdgcn_mfma_f32_16x16x32_bf16(a, b, c, 0, 0, 0); }
; template <class Epi>
; __device__ __forceinline__ void gemm_tile(const bf16_t* __restrict__ A, const bf16_t* __restrict__ Bt, int K, int row0, int col0, const Epi& epi, char* smem,
;                                           bool prefetched, bool nvalid, int nrow0, int ncol0) {
;     ...
;     for (int kt = 0; kt < nk; ++kt) {
;         const int cur = kt & 1;
;         if (kt + 1 < nk) GLDS_STAGE(cur ^ 1, pA, pB, kt + 1);
;         const char* cb = smem + cur * 2 * TILE_B;
; #pragma unroll
;         for (int ks = 0; ks < 2; ++ks) {
;             bf16x8 a[4], b[4];
; #pragma unroll
;             for (int m = 0; m < 4; ++m) a[m] = *(const bf16x8*)(cb + offA[m][ks]);
; #pragma unroll
;             for (int n = 0; n < 4; ++n) b[n] = *(const bf16x8*)(cb + offB[n][ks]);
; #pragma unroll
;             for (int m = 0; m < 4; ++m)
; #pragma unroll
;                 for (int n = 0; n < 4; ++n) acc[m][n] = mfma16(b[n], a[m], acc[m][n]);
;         }
;         asm volatile("s_waitcnt vmcnt(0)" ::: "memory");
;         __syncthreads();
.LBB0_197:
	v_readfirstlane_b32 s98, v106
	v_readfirstlane_b32 s99, v107
	v_readfirstlane_b32 s8, v108
	v_readfirstlane_b32 s100, v120
	v_readfirstlane_b32 s101, v121
	v_readfirstlane_b32 s11, v149
	s_nop 3
	s_sub_u32 s15, s8, s98
	s_and_b32 s98, s98, 0xffffff80
	s_and_b32 s100, s100, 0xffffff80
	s_nop 1
	v_subrev_u32_e32 v254, s98, v106
	v_subrev_u32_e32 v255, s100, v120
	s_add_i32 s10, s11, 0x8000
	s_mov_b32 m0, s10
	s_nop 0
	global_load_lds_dwordx4 v254, s[98:99]
	s_add_i32 m0, s10, 0x1000
	s_add_u32 s8, s98, s15
	s_addc_u32 s9, s99, 0
	global_load_lds_dwordx4 v254, s[8:9]
	s_add_i32 m0, s10, 0x2000
	s_add_u32 s8, s8, s15
	s_addc_u32 s9, s9, 0
	global_load_lds_dwordx4 v254, s[8:9]
	s_add_i32 m0, s10, 0x3000
	s_add_u32 s8, s8, s15
	s_addc_u32 s9, s9, 0
	global_load_lds_dwordx4 v254, s[8:9]
	s_add_u32 s98, s98, 0x80
	s_addc_u32 s99, s99, 0
	ds_read_b128 v[188:191], v117
	ds_read_b128 v[106:109], v130 offset:16384
	ds_read_b128 v[118:121], v130 offset:16896
	ds_read_b128 v[122:125], v130 offset:20480
	ds_read_b128 v[168:171], v130 offset:20992
	ds_read_b128 v[192:195], v117 offset:2048
	ds_read_b128 v[196:199], v117 offset:4096
	ds_read_b128 v[246:249], v117 offset:6144
.Lgk_loop_197:
	s_and_b32 s6, s1, 0x8000
	s_xor_b32 s7, s6, 0x8000
	v_or_b32_e32 v167, s6, v129
	v_add_u32_e32 v250, s6, v128
	s_add_i32 m0, s10, 0x4000
	s_nop 0
	s_waitcnt lgkmcnt(6)
	v_mfma_f32_16x16x32_bf16 v[0:3], v[106:109], v[188:191], v[0:3]
	global_load_lds_dwordx4 v255, s[100:101]
	ds_read_b128 v[172:175], v167 offset:16384
	s_waitcnt lgkmcnt(6)
	v_mfma_f32_16x16x32_bf16 v[4:7], v[118:121], v[188:191], v[4:7]
	ds_read_b128 v[176:179], v167 offset:16896
	s_add_i32 m0, s10, 0x5000
	s_add_u32 s8, s100, s15
	s_addc_u32 s9, s101, 0
	s_waitcnt lgkmcnt(6)
	v_mfma_f32_16x16x32_bf16 v[8:11], v[122:125], v[188:191], v[8:11]
	global_load_lds_dwordx4 v255, s[8:9]
	ds_read_b128 v[180:183], v167 offset:20480
	s_waitcnt lgkmcnt(6)
	v_mfma_f32_16x16x32_bf16 v[12:15], v[168:171], v[188:191], v[12:15]
	ds_read_b128 v[184:187], v167 offset:20992
	ds_read_b128 v[188:191], v250
	s_add_i32 m0, s10, 0x6000
	s_add_u32 s8, s8, s15
	s_addc_u32 s9, s9, 0
	s_waitcnt lgkmcnt(7)
	v_mfma_f32_16x16x32_bf16 v[16:19], v[106:109], v[192:195], v[16:19]
	global_load_lds_dwordx4 v255, s[8:9]
	v_mfma_f32_16x16x32_bf16 v[20:23], v[118:121], v[192:195], v[20:23]
	s_add_i32 m0, s10, 0x7000
	s_add_u32 s8, s8, s15
	s_addc_u32 s9, s9, 0
	v_mfma_f32_16x16x32_bf16 v[24:27], v[122:125], v[192:195], v[24:27]
	global_load_lds_dwordx4 v255, s[8:9]
	s_add_u32 s100, s100, 0x80
	s_addc_u32 s101, s101, 0
	v_mfma_f32_16x16x32_bf16 v[28:31], v[168:171], v[192:195], v[28:31]
	ds_read_b128 v[192:195], v250 offset:2048
	s_waitcnt lgkmcnt(7)
	v_mfma_f32_16x16x32_bf16 v[32:35], v[106:109], v[196:199], v[32:35]
	v_mfma_f32_16x16x32_bf16 v[36:39], v[118:121], v[196:199], v[36:39]
	v_mfma_f32_16x16x32_bf16 v[40:43], v[122:125], v[196:199], v[40:43]
	v_mfma_f32_16x16x32_bf16 v[44:47], v[168:171], v[196:199], v[44:47]
	ds_read_b128 v[196:199], v250 offset:4096
	s_waitcnt lgkmcnt(7)
	v_mfma_f32_16x16x32_bf16 v[48:51], v[106:109], v[246:249], v[48:51]
	v_mfma_f32_16x16x32_bf16 v[52:55], v[118:121], v[246:249], v[52:55]
	v_mfma_f32_16x16x32_bf16 v[56:59], v[122:125], v[246:249], v[56:59]
	v_mfma_f32_16x16x32_bf16 v[60:63], v[168:171], v[246:249], v[60:63]
	ds_read_b128 v[246:249], v250 offset:6144
	s_waitcnt lgkmcnt(3)
	v_mfma_f32_16x16x32_bf16 v[0:3], v[172:175], v[188:191], v[0:3]
	v_mfma_f32_16x16x32_bf16 v[4:7], v[176:179], v[188:191], v[4:7]
	v_mfma_f32_16x16x32_bf16 v[8:11], v[180:183], v[188:191], v[8:11]
	v_mfma_f32_16x16x32_bf16 v[12:15], v[184:187], v[188:191], v[12:15]
	s_waitcnt lgkmcnt(2)
	v_mfma_f32_16x16x32_bf16 v[16:19], v[172:175], v[192:195], v[16:19]
	v_mfma_f32_16x16x32_bf16 v[20:23], v[176:179], v[192:195], v[20:23]
	v_mfma_f32_16x16x32_bf16 v[24:27], v[180:183], v[192:195], v[24:27]
	v_mfma_f32_16x16x32_bf16 v[28:31], v[184:187], v[192:195], v[28:31]
	s_waitcnt vmcnt(0)
	s_waitcnt lgkmcnt(0)
	s_barrier
	s_add_i32 s1, s1, 0x8000
	s_cmp_eq_u32 s1, 0x78000
	s_cbranch_scc1 .Lgk_tail_197
	v_or_b32_e32 v167, s7, v130
	v_add_u32_e32 v250, s7, v117
	s_add_i32 s10, s6, s11
	ds_read_b128 v[188:191], v250
	ds_read_b128 v[106:109], v167 offset:16384
	s_mov_b32 m0, s10
	s_nop 0
	v_mfma_f32_16x16x32_bf16 v[32:35], v[172:175], v[196:199], v[32:35]
	global_load_lds_dwordx4 v254, s[98:99]
	ds_read_b128 v[118:121], v167 offset:16896
	v_mfma_f32_16x16x32_bf16 v[36:39], v[176:179], v[196:199], v[36:39]
	ds_read_b128 v[122:125], v167 offset:20480
	s_add_i32 m0, s10, 0x1000
	s_add_u32 s8, s98, s15
	s_addc_u32 s9, s99, 0
	v_mfma_f32_16x16x32_bf16 v[40:43], v[180:183], v[196:199], v[40:43]
	global_load_lds_dwordx4 v254, s[8:9]
	ds_read_b128 v[168:171], v167 offset:20992
	v_mfma_f32_16x16x32_bf16 v[44:47], v[184:187], v[196:199], v[44:47]
	ds_read_b128 v[192:195], v250 offset:2048
	ds_read_b128 v[196:199], v250 offset:4096
	s_add_i32 m0, s10, 0x2000
	s_add_u32 s8, s8, s15
	s_addc_u32 s9, s9, 0
	v_mfma_f32_16x16x32_bf16 v[48:51], v[172:175], v[246:249], v[48:51]
	global_load_lds_dwordx4 v254, s[8:9]
	v_mfma_f32_16x16x32_bf16 v[52:55], v[176:179], v[246:249], v[52:55]
	s_add_i32 m0, s10, 0x3000
	s_add_u32 s8, s8, s15
	s_addc_u32 s9, s9, 0
	v_mfma_f32_16x16x32_bf16 v[56:59], v[180:183], v[246:249], v[56:59]
	global_load_lds_dwordx4 v254, s[8:9]
	s_add_u32 s98, s98, 0x80
	s_addc_u32 s99, s99, 0
	v_mfma_f32_16x16x32_bf16 v[60:63], v[184:187], v[246:249], v[60:63]
	ds_read_b128 v[246:249], v250 offset:6144
	s_branch .Lgk_loop_197

; template <int KW, int VD, bool SEL> ...
;     ...
;         const bool pm = (j * 64 + 63 > tmin) || (j * 64 <= lomax);
;         bf16x8 pf[2][2];
; #pragma unroll
;         for (int qt = 0; qt < 2; ++qt) {
;             if (pm) {
;                 const bool selok = SEL ? (((((const u64*)(smem + 69632))[qt * 16 + fr] >> j) & 1ull) != 0) : true;
;                 const int t = tpos[qt], lw = lo[qt];
; #pragma unroll
;                 for (int tt = 0; tt < 4; ++tt)
; #pragma unroll
;                     for (int jj = 0; jj < 4; ++jj) {
;                         const int kp = j * 64 + 32 * (tt >> 1) + fq * 8 + (tt & 1) * 4 + jj;
;                         const bool ok = selok && (kp <= t) && (kp > lw);
;                         s[qt][tt][jj] = ok ? s[qt][tt][jj] : -1e30f;
;                     }
;             }
;             float mx = fmaxf(fmaxf(s[qt][0][0], s[qt][0][1]), fmaxf(s[qt][0][2], s[qt][0][3]));
; #pragma unroll
;             for (int tt = 1; tt < 4; ++tt) mx = fmaxf(mx, fmaxf(fmaxf(s[qt][tt][0], s[qt][tt][1]), fmaxf(s[qt][tt][2], s[qt][tt][3])));
;             const float mref = qt ? mref1 : mref0;
;             if (__builtin_amdgcn_ballot_w64(mx > (mrow[qt] - mref) + 8.0f) != 0ull) {
;                 mx = fmaxf(mx, __shfl_xor(mx, 16));
;                 mx = fmaxf(mx, __shfl_xor(mx, 32));
;                 const float mnew = fmaxf(mrow[qt], mx + mref);
;                 const float alpha = __builtin_amdgcn_exp2f(mrow[qt] - mnew);
;                 const float delta = ((mnew < -1e29f) ? 0.f : mnew) - mref;
;                 lrow[qt] *= alpha;
;                 mrow[qt] = mnew;
; #pragma unroll
;                 for (int dt = 0; dt < VD / 16; ++dt) O[qt][dt] = O[qt][dt] * alpha;
; #pragma unroll
;                 for (int tt = 0; tt < 4; ++tt)
; #pragma unroll
;                     for (int jj = 0; jj < 4; ++jj) s[qt][tt][jj] -= delta;
;             }
.LBB0_375:
	s_andn2_b64 vcc, exec, s[0:1]
	s_cbranch_vccnz .LBB0_377
	v_or_b32_e32 v170, s13, v127
	v_or_b32_e32 v169, 2, v170
	v_or_b32_e32 v168, 3, v170
	v_or_b32_e32 v167, 4, v170
	v_or_b32_e32 v166, 5, v170
	v_or_b32_e32 v165, 6, v170
	v_or_b32_e32 v164, 7, v170
	v_or_b32_e32 v163, 32, v170
	v_or_b32_e32 v162, 34, v170
	v_or_b32_e32 v145, 35, v170
	v_or_b32_e32 v144, 36, v170
	v_or_b32_e32 v143, 37, v170
	v_or_b32_e32 v142, 38, v170
	v_or_b32_e32 v141, 39, v170
	v_cmp_ne_u64_e32 vcc, 0, v[106:107]
	v_cmp_le_u32_e64 s[0:1], v170, v94
	s_and_b64 s[0:1], vcc, s[0:1]
	s_nop 0
	v_cndmask_b32_e64 v80, v85, v80, s[0:1]
	v_cmp_lt_u32_e64 s[0:1], v170, v94
	s_and_b64 s[0:1], vcc, s[0:1]
	s_nop 0
	v_cndmask_b32_e64 v81, v85, v81, s[0:1]
	v_cmp_le_u32_e64 s[0:1], v169, v94
	s_and_b64 s[0:1], vcc, s[0:1]
	s_nop 0
	v_cndmask_b32_e64 v82, v85, v82, s[0:1]
	v_cmp_le_u32_e64 s[0:1], v168, v94
	s_and_b64 s[0:1], vcc, s[0:1]
	s_nop 0
	v_cndmask_b32_e64 v83, v85, v83, s[0:1]
	v_cmp_le_u32_e64 s[0:1], v167, v94
	s_and_b64 s[0:1], vcc, s[0:1]
	s_nop 0
	v_cndmask_b32_e64 v72, v85, v72, s[0:1]
	v_cmp_le_u32_e64 s[0:1], v166, v94
	s_and_b64 s[0:1], vcc, s[0:1]
	s_nop 0
	v_cndmask_b32_e64 v73, v85, v73, s[0:1]
	v_cmp_le_u32_e64 s[0:1], v165, v94
	s_and_b64 s[0:1], vcc, s[0:1]
	s_nop 0
	v_cndmask_b32_e64 v74, v85, v74, s[0:1]
	v_cmp_le_u32_e64 s[0:1], v164, v94
	s_and_b64 s[0:1], vcc, s[0:1]
	s_nop 0
	v_cndmask_b32_e64 v75, v85, v75, s[0:1]
	v_cmp_le_u32_e64 s[0:1], v163, v94
	s_and_b64 s[0:1], vcc, s[0:1]
	s_nop 0
	v_cndmask_b32_e64 v76, v85, v76, s[0:1]
	v_cmp_lt_u32_e64 s[0:1], v163, v94
	s_and_b64 s[0:1], vcc, s[0:1]
	s_nop 0
	v_cndmask_b32_e64 v77, v85, v77, s[0:1]
	v_cmp_le_u32_e64 s[0:1], v162, v94
	s_and_b64 s[0:1], vcc, s[0:1]
	s_nop 0
	v_cndmask_b32_e64 v78, v85, v78, s[0:1]
	v_cmp_le_u32_e64 s[0:1], v145, v94
	s_and_b64 s[0:1], vcc, s[0:1]
	s_nop 0
	v_cndmask_b32_e64 v79, v85, v79, s[0:1]
	v_cmp_le_u32_e64 s[0:1], v144, v94
	s_and_b64 s[0:1], vcc, s[0:1]
	s_nop 0
	v_cndmask_b32_e64 v68, v85, v68, s[0:1]
	v_cmp_le_u32_e64 s[0:1], v143, v94
	s_and_b64 s[0:1], vcc, s[0:1]
	s_nop 0
	v_cndmask_b32_e64 v69, v85, v69, s[0:1]
	v_cmp_le_u32_e64 s[0:1], v142, v94
	s_and_b64 s[0:1], vcc, s[0:1]
	s_nop 0
	v_cndmask_b32_e64 v70, v85, v70, s[0:1]
	v_cmp_le_u32_e64 s[0:1], v141, v94
	s_and_b64 vcc, vcc, s[0:1]
	v_cndmask_b32_e32 v71, v85, v71, vcc
.LBB0_377:
	v_max3_f32 v106, v80, v81, v82
	v_max3_f32 v107, v83, v72, v73
	v_max3_f32 v106, v106, v74, v75
	v_max3_f32 v107, v107, v76, v77
	v_max3_f32 v106, v106, v78, v79
	v_max3_f32 v107, v107, v68, v69
	v_max3_f32 v106, v106, v70, v71
	v_max_f32_e32 v106, v106, v107
	v_sub_f32_e32 v107, v130, v171
	v_add_f32_e32 v107, 0x41000000, v107
	v_cmp_gt_f32_e32 vcc, v106, v107
	s_cbranch_vccz .LBB0_379
	ds_bpermute_b32 v107, v119, v106
	v_max_f32_e32 v106, v106, v106
	v_max_f32_e32 v172, v130, v130
	s_waitcnt lgkmcnt(0)
	v_max_f32_e32 v107, v107, v107
	v_max_f32_e32 v106, v106, v107
	ds_bpermute_b32 v107, v118, v106
	s_waitcnt lgkmcnt(0)
	v_max_f32_e32 v107, v107, v107
	v_max_f32_e32 v106, v106, v107
	v_add_f32_e32 v106, v171, v106
	v_max_f32_e32 v107, v172, v106
	v_sub_f32_e32 v106, v130, v107
	v_exp_f32_e32 v106, v106
	v_cmp_ngt_f32_e32 vcc, s16, v107
	v_mul_f32_e32 v105, v105, v106
	s_nop 0
	v_cndmask_b32_e32 v130, 0, v107, vcc
	v_pk_mul_f32 v[50:51], v[50:51], v[106:107] op_sel_hi:[1,0]
	v_pk_mul_f32 v[48:49], v[48:49], v[106:107] op_sel_hi:[1,0]
	v_pk_mul_f32 v[46:47], v[46:47], v[106:107] op_sel_hi:[1,0]
	v_pk_mul_f32 v[44:45], v[44:45], v[106:107] op_sel_hi:[1,0]
	v_pk_mul_f32 v[42:43], v[42:43], v[106:107] op_sel_hi:[1,0]
	v_pk_mul_f32 v[40:41], v[40:41], v[106:107] op_sel_hi:[1,0]
	v_pk_mul_f32 v[38:39], v[38:39], v[106:107] op_sel_hi:[1,0]
	v_pk_mul_f32 v[36:37], v[36:37], v[106:107] op_sel_hi:[1,0]
	v_sub_f32_e32 v106, v130, v171
	v_pk_add_f32 v[80:81], v[80:81], v[106:107] op_sel_hi:[1,0] neg_lo:[0,1] neg_hi:[0,1]
	v_pk_add_f32 v[82:83], v[82:83], v[106:107] op_sel_hi:[1,0] neg_lo:[0,1] neg_hi:[0,1]
	v_pk_add_f32 v[72:73], v[72:73], v[106:107] op_sel_hi:[1,0] neg_lo:[0,1] neg_hi:[0,1]
	v_pk_add_f32 v[74:75], v[74:75], v[106:107] op_sel_hi:[1,0] neg_lo:[0,1] neg_hi:[0,1]
	v_pk_add_f32 v[76:77], v[76:77], v[106:107] op_sel_hi:[1,0] neg_lo:[0,1] neg_hi:[0,1]
	v_pk_add_f32 v[78:79], v[78:79], v[106:107] op_sel_hi:[1,0] neg_lo:[0,1] neg_hi:[0,1]
	v_pk_add_f32 v[68:69], v[68:69], v[106:107] op_sel_hi:[1,0] neg_lo:[0,1] neg_hi:[0,1]
	v_pk_add_f32 v[70:71], v[70:71], v[106:107] op_sel_hi:[1,0] neg_lo:[0,1] neg_hi:[0,1]
	v_mov_b32_e32 v130, v107

; template <int KW, int VD, bool SEL> ...
;     ...
;         if (tiles) { jn = __ffsll((long long)tiles) - 1; tiles &= tiles - 1; FL_ISSUE(cur ^ 1, jn); }
;         const char* sK = smem + cur * BUFB;
;         const char* sV = smem + cur * BUFB + KB;
;         f32x4 s[2][4];
;         const float mref0 = (mrow[0] < -1e29f) ? 0.f : mrow[0], mref1 = (mrow[1] < -1e29f) ? 0.f : mrow[1];
;         const float ci0 = (SEL && !((((const u64*)(smem + 69632))[fr] >> j) & 1ull)) ? -1e30f : -mref0;
;         const float ci1 = (SEL && !((((const u64*)(smem + 69632))[16 + fr] >> j) & 1ull)) ? -1e30f : -mref1;
;         const f32x4 cinit0 = (f32x4){ci0, ci0, ci0, ci0}, cinit1 = (f32x4){ci1, ci1, ci1, ci1};
; #pragma unroll
;         for (int tt = 0; tt < 4; ++tt) {
;             const int kr = 32 * (tt >> 1) + (fr >> 2) * 8 + (tt & 1) * 4 + (fr & 3);
;             const bf16x8 kf0 = *(const bf16x8*)(sK + kr * KROWB + (((kcol >> 3) + fq) ^ kswz) * 16);
;             const bf16x8 kf1 = *(const bf16x8*)(sK + kr * KROWB + (((kcol >> 3) + 4 + fq) ^ kswz) * 16);
.LBB0_394:
	v_add_u32_e32 v3, s13, v127
	v_add_u32_e32 v129, v3, v123
	ds_read_b128 v[52:55], v129
	ds_read_b128 v[60:63], v129 offset:512
	v_cmp_ngt_f32_e32 vcc, s16, v0
	v_add_u32_e32 v3, v3, v124
	ds_read_b128 v[68:71], v3
	ds_read_b128 v[72:75], v3 offset:512
	s_cmp_lt_i32 s12, 0
	s_cbranch_scc1 .Lfh_win_nodma
	v_readfirstlane_b32 s0, v106
	s_mul_i32 s14, s12, 0x44000
	s_add_u32 s14, s6, s14
	s_addc_u32 s15, s7, 0
	s_add_u32 s14, s14, 0xe00
	s_addc_u32 s15, s15, 0
	s_lshl_b32 s5, s12, 7
	s_add_u32 s22, s8, s5
	s_addc_u32 s23, s9, 0
	s_xor_b32 s5, s13, 0x4000
	s_add_i32 s5, s5, s0
	s_mov_b32 m0, s5
	s_nop 0
	global_load_lds_dwordx4 v250, s[14:15]
	s_add_i32 m0, s5, 0x1000
	s_nop 0
	global_load_lds_dwordx4 v251, s[14:15]
	s_add_i32 m0, s5, 0x2000
	s_nop 0
	global_load_lds_dwordx4 v252, s[22:23]
	s_add_i32 m0, s5, 0x3000
	s_nop 0
	global_load_lds_dwordx4 v253, s[22:23]

; template <int KW, int VD, bool SEL> ...
;     ...
;         const bool pm = (j * 64 + 63 > tmin) || (j * 64 <= lomax);
;         bf16x8 pf[2][2];
; #pragma unroll
;         for (int qt = 0; qt < 2; ++qt) {
;             if (pm) {
;                 const bool selok = SEL ? (((((const u64*)(smem + 69632))[qt * 16 + fr] >> j) & 1ull) != 0) : true;
;                 const int t = tpos[qt], lw = lo[qt];
; #pragma unroll
;                 for (int tt = 0; tt < 4; ++tt)
; #pragma unroll
;                     for (int jj = 0; jj < 4; ++jj) {
;                         const int kp = j * 64 + 32 * (tt >> 1) + fq * 8 + (tt & 1) * 4 + jj;
;                         const bool ok = selok && (kp <= t) && (kp > lw);
;                         s[qt][tt][jj] = ok ? s[qt][tt][jj] : -1e30f;
;                     }
;             }
;             float mx = fmaxf(fmaxf(s[qt][0][0], s[qt][0][1]), fmaxf(s[qt][0][2], s[qt][0][3]));
; #pragma unroll
;             for (int tt = 1; tt < 4; ++tt) mx = fmaxf(mx, fmaxf(fmaxf(s[qt][tt][0], s[qt][tt][1]), fmaxf(s[qt][tt][2], s[qt][tt][3])));
;             const float mref = qt ? mref1 : mref0;
;             if (__builtin_amdgcn_ballot_w64(mx > (mrow[qt] - mref) + 8.0f) != 0ull) {
;                 mx = fmaxf(mx, __shfl_xor(mx, 16));
;                 mx = fmaxf(mx, __shfl_xor(mx, 32));
;                 const float mnew = fmaxf(mrow[qt], mx + mref);
;                 const float alpha = __builtin_amdgcn_exp2f(mrow[qt] - mnew);
;                 const float delta = ((mnew < -1e29f) ? 0.f : mnew) - mref;
;                 lrow[qt] *= alpha;
;                 mrow[qt] = mnew;
; #pragma unroll
;                 for (int dt = 0; dt < VD / 16; ++dt) O[qt][dt] = O[qt][dt] * alpha;
; #pragma unroll
;                 for (int tt = 0; tt < 4; ++tt)
; #pragma unroll
;                     for (int jj = 0; jj < 4; ++jj) s[qt][tt][jj] -= delta;
;             }
.LBB0_396:
	s_andn2_b64 vcc, exec, s[0:1]
	s_cbranch_vccnz .LBB0_398
	v_or_b32_e32 v166, s14, v125
	v_or_b32_e32 v165, 2, v166
	v_or_b32_e32 v164, 3, v166
	v_or_b32_e32 v163, 4, v166
	v_or_b32_e32 v162, 5, v166
	v_or_b32_e32 v145, 6, v166
	v_or_b32_e32 v144, 7, v166
	v_or_b32_e32 v143, 32, v166
	v_or_b32_e32 v142, 34, v166
	v_or_b32_e32 v141, 35, v166
	v_or_b32_e32 v131, 36, v166
	v_or_b32_e32 v130, 37, v166
	v_or_b32_e32 v129, 38, v166
	v_or_b32_e32 v3, 39, v166
	v_cmp_le_u32_e32 vcc, v166, v94
	v_cmp_gt_i32_e64 s[0:1], v166, v107
	s_and_b64 vcc, vcc, s[0:1]
	v_cndmask_b32_e32 v80, v85, v80, vcc
	v_cmp_lt_u32_e32 vcc, v166, v94
	v_cmp_ge_i32_e64 s[0:1], v166, v107
	s_and_b64 vcc, vcc, s[0:1]
	v_cndmask_b32_e32 v81, v85, v81, vcc
	v_cmp_le_u32_e32 vcc, v165, v94
	v_cmp_gt_i32_e64 s[0:1], v165, v107
	s_and_b64 vcc, vcc, s[0:1]
	v_cndmask_b32_e32 v82, v85, v82, vcc
	v_cmp_le_u32_e32 vcc, v164, v94
	v_cmp_gt_i32_e64 s[0:1], v164, v107
	s_and_b64 vcc, vcc, s[0:1]
	v_cndmask_b32_e32 v83, v85, v83, vcc
	v_cmp_le_u32_e32 vcc, v163, v94
	v_cmp_gt_i32_e64 s[0:1], v163, v107
	s_and_b64 vcc, vcc, s[0:1]
	v_cndmask_b32_e32 v68, v85, v68, vcc
	v_cmp_le_u32_e32 vcc, v162, v94
	v_cmp_gt_i32_e64 s[0:1], v162, v107
	s_and_b64 vcc, vcc, s[0:1]
	v_cndmask_b32_e32 v69, v85, v69, vcc
	v_cmp_le_u32_e32 vcc, v145, v94
	v_cmp_gt_i32_e64 s[0:1], v145, v107
	s_and_b64 vcc, vcc, s[0:1]
	v_cndmask_b32_e32 v70, v85, v70, vcc
	v_cmp_le_u32_e32 vcc, v144, v94
	v_cmp_gt_i32_e64 s[0:1], v144, v107
	s_and_b64 vcc, vcc, s[0:1]
	v_cndmask_b32_e32 v71, v85, v71, vcc
	v_cmp_le_u32_e32 vcc, v143, v94
	v_cmp_gt_i32_e64 s[0:1], v143, v107
	s_and_b64 vcc, vcc, s[0:1]
	v_cndmask_b32_e32 v72, v85, v72, vcc
	v_cmp_lt_u32_e32 vcc, v143, v94
	v_cmp_ge_i32_e64 s[0:1], v143, v107
	s_and_b64 vcc, vcc, s[0:1]
	v_cndmask_b32_e32 v73, v85, v73, vcc
	v_cmp_le_u32_e32 vcc, v142, v94
	v_cmp_gt_i32_e64 s[0:1], v142, v107
	s_and_b64 vcc, vcc, s[0:1]
	v_cndmask_b32_e32 v74, v85, v74, vcc
	v_cmp_le_u32_e32 vcc, v141, v94
	v_cmp_gt_i32_e64 s[0:1], v141, v107
	s_and_b64 vcc, vcc, s[0:1]
	v_cndmask_b32_e32 v75, v85, v75, vcc
	v_cmp_le_u32_e32 vcc, v131, v94
	v_cmp_gt_i32_e64 s[0:1], v131, v107
	s_and_b64 vcc, vcc, s[0:1]
	v_cndmask_b32_e32 v76, v85, v76, vcc
	v_cmp_le_u32_e32 vcc, v130, v94
	v_cmp_gt_i32_e64 s[0:1], v130, v107
	s_and_b64 vcc, vcc, s[0:1]
	v_cndmask_b32_e32 v77, v85, v77, vcc
	v_cmp_le_u32_e32 vcc, v129, v94
	v_cmp_gt_i32_e64 s[0:1], v129, v107
	s_and_b64 vcc, vcc, s[0:1]
	v_cndmask_b32_e32 v78, v85, v78, vcc
	v_cmp_le_u32_e32 vcc, v3, v94
	v_cmp_gt_i32_e64 s[0:1], v3, v107
	s_and_b64 vcc, vcc, s[0:1]
	v_cndmask_b32_e32 v79, v85, v79, vcc
.LBB0_398:
	v_max3_f32 v168, v80, v81, v82
	v_max3_f32 v169, v83, v68, v69
	v_max3_f32 v168, v168, v70, v71
	v_max3_f32 v169, v169, v72, v73
	v_max3_f32 v168, v168, v74, v75
	v_max3_f32 v169, v169, v76, v77
	v_max3_f32 v168, v168, v78, v79
	v_max_f32_e32 v168, v168, v169
	v_sub_f32_e32 v169, v0, v167
	v_add_f32_e32 v169, 0x41000000, v169
	v_cmp_gt_f32_e32 vcc, v168, v169
	s_cbranch_vccz .LBB0_400
	ds_bpermute_b32 v169, v119, v168
	v_max_f32_e32 v168, v168, v168
	v_max_f32_e32 v170, v0, v0
	s_waitcnt lgkmcnt(0)
	v_max_f32_e32 v169, v169, v169
	v_max_f32_e32 v168, v168, v169
	ds_bpermute_b32 v169, v118, v168
	s_waitcnt lgkmcnt(0)
	v_max_f32_e32 v169, v169, v169
	v_max_f32_e32 v168, v168, v169
	v_add_f32_e32 v168, v167, v168
	v_max_f32_e32 v168, v170, v168
	v_sub_f32_e32 v0, v0, v168
	v_exp_f32_e32 v0, v0
	v_cmp_ngt_f32_e32 vcc, s16, v168
	v_mul_f32_e32 v105, v105, v0
	s_nop 0
	v_cndmask_b32_e32 v169, 0, v168, vcc
	v_pk_mul_f32 v[50:51], v[50:51], v[0:1] op_sel_hi:[1,0]
	v_pk_mul_f32 v[48:49], v[48:49], v[0:1] op_sel_hi:[1,0]
	v_pk_mul_f32 v[46:47], v[46:47], v[0:1] op_sel_hi:[1,0]
	v_pk_mul_f32 v[44:45], v[44:45], v[0:1] op_sel_hi:[1,0]
	v_pk_mul_f32 v[42:43], v[42:43], v[0:1] op_sel_hi:[1,0]
	v_pk_mul_f32 v[40:41], v[40:41], v[0:1] op_sel_hi:[1,0]
	v_pk_mul_f32 v[38:39], v[38:39], v[0:1] op_sel_hi:[1,0]
	v_pk_mul_f32 v[36:37], v[36:37], v[0:1] op_sel_hi:[1,0]
	v_sub_f32_e32 v0, v169, v167
	v_pk_add_f32 v[80:81], v[80:81], v[0:1] op_sel_hi:[1,0] neg_lo:[0,1] neg_hi:[0,1]
	v_pk_add_f32 v[82:83], v[82:83], v[0:1] op_sel_hi:[1,0] neg_lo:[0,1] neg_hi:[0,1]
	v_pk_add_f32 v[68:69], v[68:69], v[0:1] op_sel_hi:[1,0] neg_lo:[0,1] neg_hi:[0,1]
	v_pk_add_f32 v[70:71], v[70:71], v[0:1] op_sel_hi:[1,0] neg_lo:[0,1] neg_hi:[0,1]
	v_pk_add_f32 v[72:73], v[72:73], v[0:1] op_sel_hi:[1,0] neg_lo:[0,1] neg_hi:[0,1]
	v_pk_add_f32 v[74:75], v[74:75], v[0:1] op_sel_hi:[1,0] neg_lo:[0,1] neg_hi:[0,1]
	v_pk_add_f32 v[76:77], v[76:77], v[0:1] op_sel_hi:[1,0] neg_lo:[0,1] neg_hi:[0,1]
	v_pk_add_f32 v[78:79], v[78:79], v[0:1] op_sel_hi:[1,0] neg_lo:[0,1] neg_hi:[0,1]
	v_mov_b32_e32 v0, v168

; __device__ __forceinline__ f32x4 mfma16(bf16x8 a, bf16x8 b, f32x4 c) { return __builtin_amdgcn_mfma_f32_16x16x32_bf16(a, b, c, 0, 0, 0); }
; template <class Epi>
; __device__ __forceinline__ void gemm_tile(const bf16_t* __restrict__ A, const bf16_t* __restrict__ Bt, int K, int row0, int col0, const Epi& epi, char* smem,
;                                           bool prefetched, bool nvalid, int nrow0, int ncol0) {
;     ...
;     for (int kt = 0; kt < nk; ++kt) {
;         const int cur = kt & 1;
;         if (kt + 1 < nk) GLDS_STAGE(cur ^ 1, pA, pB, kt + 1);
;         const char* cb = smem + cur * 2 * TILE_B;
; #pragma unroll
;         for (int ks = 0; ks < 2; ++ks) {
;             bf16x8 a[4], b[4];
; #pragma unroll
;             for (int m = 0; m < 4; ++m) a[m] = *(const bf16x8*)(cb + offA[m][ks]);
; #pragma unroll
;             for (int n = 0; n < 4; ++n) b[n] = *(const bf16x8*)(cb + offB[n][ks]);
; #pragma unroll
;             for (int m = 0; m < 4; ++m)
; #pragma unroll
;                 for (int n = 0; n < 4; ++n) acc[m][n] = mfma16(b[n], a[m], acc[m][n]);
;         }
;         asm volatile("s_waitcnt vmcnt(0)" ::: "memory");
;         __syncthreads();
.LBB0_460:
	v_readfirstlane_b32 s98, v94
	v_readfirstlane_b32 s99, v95
	v_readfirstlane_b32 s8, v96
	v_readfirstlane_b32 s100, v102
	v_readfirstlane_b32 s101, v103
	v_readfirstlane_b32 s12, v149
	s_nop 3
	s_sub_u32 s13, s8, s98
	s_and_b32 s98, s98, 0xffffff80
	s_and_b32 s100, s100, 0xffffff80
	s_nop 1
	v_subrev_u32_e32 v254, s98, v94
	v_subrev_u32_e32 v255, s100, v102
	s_add_i32 s11, s12, 0x8000
	s_mov_b32 m0, s11
	s_nop 0
	global_load_lds_dwordx4 v254, s[98:99]
	s_add_i32 m0, s11, 0x1000
	s_add_u32 s8, s98, s13
	s_addc_u32 s9, s99, 0
	global_load_lds_dwordx4 v254, s[8:9]
	s_add_i32 m0, s11, 0x2000
	s_add_u32 s8, s8, s13
	s_addc_u32 s9, s9, 0
	global_load_lds_dwordx4 v254, s[8:9]
	s_add_i32 m0, s11, 0x3000
	s_add_u32 s8, s8, s13
	s_addc_u32 s9, s9, 0
	global_load_lds_dwordx4 v254, s[8:9]
	s_add_u32 s98, s98, 0x80
	s_addc_u32 s99, s99, 0
	ds_read_b128 v[174:177], v110
	ds_read_b128 v[94:97], v87 offset:16384
	ds_read_b128 v[98:101], v87 offset:16896
	ds_read_b128 v[102:105], v87 offset:20480
	ds_read_b128 v[106:109], v87 offset:20992
	ds_read_b128 v[178:181], v110 offset:2048
	ds_read_b128 v[246:249], v110 offset:4096
	ds_read_b128 v[250:253], v110 offset:6144
.Lgk_loop_460:
	s_and_b32 s5, s1, 0x8000
	s_xor_b32 s10, s5, 0x8000
	v_or_b32_e32 v130, s5, v118
	v_add_u32_e32 v131, s5, v111
	s_add_i32 m0, s11, 0x4000
	s_nop 0
	s_waitcnt lgkmcnt(6)
	v_mfma_f32_16x16x32_bf16 v[0:3], v[94:97], v[174:177], v[0:3]
	global_load_lds_dwordx4 v255, s[100:101]
	ds_read_b128 v[142:145], v130 offset:16384
	s_waitcnt lgkmcnt(6)
	v_mfma_f32_16x16x32_bf16 v[4:7], v[98:101], v[174:177], v[4:7]
	ds_read_b128 v[162:165], v130 offset:16896
	s_add_i32 m0, s11, 0x5000
	s_add_u32 s8, s100, s13
	s_addc_u32 s9, s101, 0
	s_waitcnt lgkmcnt(6)
	v_mfma_f32_16x16x32_bf16 v[8:11], v[102:105], v[174:177], v[8:11]
	global_load_lds_dwordx4 v255, s[8:9]
	ds_read_b128 v[166:169], v130 offset:20480
	s_waitcnt lgkmcnt(6)
	v_mfma_f32_16x16x32_bf16 v[12:15], v[106:109], v[174:177], v[12:15]
	ds_read_b128 v[170:173], v130 offset:20992
	ds_read_b128 v[174:177], v131
	s_add_i32 m0, s11, 0x6000
	s_add_u32 s8, s8, s13
	s_addc_u32 s9, s9, 0
	s_waitcnt lgkmcnt(7)
	v_mfma_f32_16x16x32_bf16 v[16:19], v[94:97], v[178:181], v[16:19]
	global_load_lds_dwordx4 v255, s[8:9]
	v_mfma_f32_16x16x32_bf16 v[20:23], v[98:101], v[178:181], v[20:23]
	s_add_i32 m0, s11, 0x7000
	s_add_u32 s8, s8, s13
	s_addc_u32 s9, s9, 0
	v_mfma_f32_16x16x32_bf16 v[24:27], v[102:105], v[178:181], v[24:27]
	global_load_lds_dwordx4 v255, s[8:9]
	s_add_u32 s100, s100, 0x80
	s_addc_u32 s101, s101, 0
	v_mfma_f32_16x16x32_bf16 v[28:31], v[106:109], v[178:181], v[28:31]
	ds_read_b128 v[178:181], v131 offset:2048
	s_waitcnt lgkmcnt(7)
	v_mfma_f32_16x16x32_bf16 v[32:35], v[94:97], v[246:249], v[32:35]
	v_mfma_f32_16x16x32_bf16 v[36:39], v[98:101], v[246:249], v[36:39]
	v_mfma_f32_16x16x32_bf16 v[40:43], v[102:105], v[246:249], v[40:43]
	v_mfma_f32_16x16x32_bf16 v[44:47], v[106:109], v[246:249], v[44:47]
	ds_read_b128 v[246:249], v131 offset:4096
	s_waitcnt lgkmcnt(7)
	v_mfma_f32_16x16x32_bf16 v[48:51], v[94:97], v[250:253], v[48:51]
	v_mfma_f32_16x16x32_bf16 v[52:55], v[98:101], v[250:253], v[52:55]
	v_mfma_f32_16x16x32_bf16 v[56:59], v[102:105], v[250:253], v[56:59]
	v_mfma_f32_16x16x32_bf16 v[60:63], v[106:109], v[250:253], v[60:63]
	ds_read_b128 v[250:253], v131 offset:6144
	s_waitcnt lgkmcnt(3)
	v_mfma_f32_16x16x32_bf16 v[0:3], v[142:145], v[174:177], v[0:3]
	v_mfma_f32_16x16x32_bf16 v[4:7], v[162:165], v[174:177], v[4:7]
	v_mfma_f32_16x16x32_bf16 v[8:11], v[166:169], v[174:177], v[8:11]
	v_mfma_f32_16x16x32_bf16 v[12:15], v[170:173], v[174:177], v[12:15]
	s_waitcnt lgkmcnt(2)
	v_mfma_f32_16x16x32_bf16 v[16:19], v[142:145], v[178:181], v[16:19]
	v_mfma_f32_16x16x32_bf16 v[20:23], v[162:165], v[178:181], v[20:23]
	v_mfma_f32_16x16x32_bf16 v[24:27], v[166:169], v[178:181], v[24:27]
	v_mfma_f32_16x16x32_bf16 v[28:31], v[170:173], v[178:181], v[28:31]
	s_waitcnt vmcnt(0)
	s_waitcnt lgkmcnt(0)
	s_barrier
	s_add_i32 s1, s1, 0x8000
	s_cmp_eq_u32 s1, 0x78000
	s_cbranch_scc1 .Lgk_tail_460
	v_or_b32_e32 v130, s10, v87
	v_add_u32_e32 v131, s10, v110
	s_add_i32 s11, s5, s12
	ds_read_b128 v[174:177], v131
	ds_read_b128 v[94:97], v130 offset:16384
	s_mov_b32 m0, s11
	s_nop 0
	v_mfma_f32_16x16x32_bf16 v[32:35], v[142:145], v[246:249], v[32:35]
	global_load_lds_dwordx4 v254, s[98:99]
	ds_read_b128 v[98:101], v130 offset:16896
	v_mfma_f32_16x16x32_bf16 v[36:39], v[162:165], v[246:249], v[36:39]
	ds_read_b128 v[102:105], v130 offset:20480
	s_add_i32 m0, s11, 0x1000
	s_add_u32 s8, s98, s13
	s_addc_u32 s9, s99, 0
	v_mfma_f32_16x16x32_bf16 v[40:43], v[166:169], v[246:249], v[40:43]
	global_load_lds_dwordx4 v254, s[8:9]
	ds_read_b128 v[106:109], v130 offset:20992
	v_mfma_f32_16x16x32_bf16 v[44:47], v[170:173], v[246:249], v[44:47]
	ds_read_b128 v[178:181], v131 offset:2048
	ds_read_b128 v[246:249], v131 offset:4096
	s_add_i32 m0, s11, 0x2000
	s_add_u32 s8, s8, s13
	s_addc_u32 s9, s9, 0
	v_mfma_f32_16x16x32_bf16 v[48:51], v[142:145], v[250:253], v[48:51]
	global_load_lds_dwordx4 v254, s[8:9]
	v_mfma_f32_16x16x32_bf16 v[52:55], v[162:165], v[250:253], v[52:55]
	s_add_i32 m0, s11, 0x3000
	s_add_u32 s8, s8, s13
	s_addc_u32 s9, s9, 0
	v_mfma_f32_16x16x32_bf16 v[56:59], v[166:169], v[250:253], v[56:59]
	global_load_lds_dwordx4 v254, s[8:9]
	s_add_u32 s98, s98, 0x80
	s_addc_u32 s99, s99, 0
	v_mfma_f32_16x16x32_bf16 v[60:63], v[170:173], v[250:253], v[60:63]
	ds_read_b128 v[250:253], v131 offset:6144
	s_branch .Lgk_loop_460

; __device__ __forceinline__ u32x2 pack4(f32x4 v) { u32x2 r; r.x = cvt_pk_bf16(v[0], v[1]); r.y = cvt_pk_bf16(v[2], v[3]); return r; }
; __device__ __forceinline__ void rmsnorm_phase(const float* x, const float* g, bf16_t* outb, float* outf) {
;     ...
;     for (int row = gw; row < T; row += nw) {
;         const float* xr = x + (size_t)row * D;
;         f32x4 v[4];
;         float ss = 0.f;
; #pragma unroll
;         for (int i = 0; i < 4; ++i) { v[i] = __builtin_nontemporal_load((const f32x4*)(xr + (lane + i * 64) * 4)); ss += v[i][0] * v[i][0] + v[i][1] * v[i][1] + v[i][2] * v[i][2] + v[i][3] * v[i][3]; }
; #pragma unroll
;         for (int o = 32; o >= 1; o >>= 1) ss += __shfl_xor(ss, o);
;         const float r = rsqrtf(ss * (1.0f / D) + EPS);
; #pragma unroll
;         for (int i = 0; i < 4; ++i) {
;             const f32x4 y = v[i] * r * gv[i];
;             if (outb) *(u32x2*)(outb + (size_t)row * D + (lane + i * 64) * 4) = pack4(y);
;             else __builtin_nontemporal_store(y, (f32x4*)(outf + (size_t)row * D + (lane + i * 64) * 4));
;         }
;     }
.LBB0_510:
	global_load_dwordx4 v[28:31], v[18:19], off offset:-3072 nt
	global_load_dwordx4 v[32:35], v[18:19], off offset:-2048 nt
	global_load_dwordx4 v[36:39], v[18:19], off offset:-1024 nt
	global_load_dwordx4 v[40:43], v[18:19], off nt
	v_add_u32_e32 v27, s40, v27
	v_cmp_lt_i32_e32 vcc, s11, v27
	s_or_b64 s[8:9], vcc, s[8:9]
	v_lshl_add_u64 v[18:19], v[18:19], 0, s[6:7]
	s_waitcnt vmcnt(0)
	v_mov_b32_e32 v46, v29
	v_mov_b32_e32 v47, v33
	v_mov_b32_e32 v44, v28
	v_mov_b32_e32 v45, v32
	v_mov_b32_e32 v54, v37
	v_mov_b32_e32 v55, v41
	v_pk_mul_f32 v[46:47], v[46:47], v[46:47]
	v_mov_b32_e32 v48, v30
	v_mov_b32_e32 v49, v34
	v_mov_b32_e32 v52, v36
	v_mov_b32_e32 v53, v40
	v_pk_mul_f32 v[54:55], v[54:55], v[54:55]
	v_pk_fma_f32 v[44:45], v[44:45], v[44:45], v[46:47]
	v_mov_b32_e32 v50, v31
	v_mov_b32_e32 v51, v35
	v_mov_b32_e32 v56, v38
	v_mov_b32_e32 v57, v42
	v_pk_fma_f32 v[46:47], v[52:53], v[52:53], v[54:55]
	v_pk_fma_f32 v[44:45], v[48:49], v[48:49], v[44:45]
	v_mov_b32_e32 v58, v39
	v_mov_b32_e32 v59, v43
	v_pk_fma_f32 v[46:47], v[56:57], v[56:57], v[46:47]
	v_pk_fma_f32 v[44:45], v[50:51], v[50:51], v[44:45]
	v_pk_fma_f32 v[46:47], v[58:59], v[58:59], v[46:47]
	v_add_f32_e32 v44, v44, v45
	v_add_f32_e32 v44, v44, v46
	v_add_f32_e32 v44, v44, v47
	v_mov_b32_e32 v45, v44
	s_nop 1
	v_permlane32_swap_b32_e32 v44, v45
	v_add_f32_e32 v44, v44, v45
	v_mov_b32_e32 v45, v44
	s_nop 1
	v_permlane16_swap_b32_e32 v44, v45
	v_add_f32_e32 v44, v44, v45
	s_nop 1
	v_add_f32_dpp v44, v44, v44 row_ror:8 row_mask:0xf bank_mask:0xf
	s_nop 1
	v_add_f32_dpp v44, v44, v44 row_ror:4 row_mask:0xf bank_mask:0xf
	s_nop 1
	v_add_f32_dpp v44, v44, v44 quad_perm:[2,3,0,1] row_mask:0xf bank_mask:0xf
	s_nop 1
	v_add_f32_dpp v44, v44, v44 quad_perm:[1,0,3,2] row_mask:0xf bank_mask:0xf
	v_fmamk_f32 v44, v44, 0x3a800000, v26
	v_mul_f32_e32 v45, 0x4b800000, v44
	v_cmp_gt_f32_e32 vcc, s10, v44
	s_nop 1
	v_cndmask_b32_e32 v44, v44, v45, vcc
	v_rsq_f32_e32 v44, v44
	s_nop 0
	v_mul_f32_e32 v45, 0x45800000, v44
	v_cndmask_b32_e32 v44, v44, v45, vcc
	v_pk_mul_f32 v[28:29], v[28:29], v[44:45] op_sel_hi:[1,0]
	v_pk_mul_f32 v[30:31], v[30:31], v[44:45] op_sel_hi:[1,0]
	v_pk_mul_f32 v[32:33], v[32:33], v[44:45] op_sel_hi:[1,0]
	v_pk_mul_f32 v[34:35], v[34:35], v[44:45] op_sel_hi:[1,0]
	v_pk_mul_f32 v[36:37], v[36:37], v[44:45] op_sel_hi:[1,0]
	v_pk_mul_f32 v[38:39], v[38:39], v[44:45] op_sel_hi:[1,0]
	v_pk_mul_f32 v[40:41], v[40:41], v[44:45] op_sel_hi:[1,0]
	v_pk_mul_f32 v[42:43], v[42:43], v[44:45] op_sel_hi:[1,0]
	v_pk_mul_f32 v[30:31], v[2:3], v[30:31]
	v_pk_mul_f32 v[28:29], v[0:1], v[28:29]
	v_pk_mul_f32 v[34:35], v[6:7], v[34:35]
	v_pk_mul_f32 v[32:33], v[4:5], v[32:33]
	v_pk_mul_f32 v[38:39], v[10:11], v[38:39]
	v_pk_mul_f32 v[36:37], v[8:9], v[36:37]
	v_pk_mul_f32 v[42:43], v[14:15], v[42:43]
	v_pk_mul_f32 v[40:41], v[12:13], v[40:41]
	v_cvt_pk_bf16_f32 v28, v28, v29
	v_cvt_pk_bf16_f32 v29, v30, v31
	v_cvt_pk_bf16_f32 v30, v32, v33
	v_cvt_pk_bf16_f32 v31, v34, v35
	v_cvt_pk_bf16_f32 v32, v36, v37
	v_cvt_pk_bf16_f32 v33, v38, v39
	v_cvt_pk_bf16_f32 v34, v40, v41
	v_cvt_pk_bf16_f32 v35, v42, v43
	global_store_dwordx2 v[16:17], v[28:29], off
	global_store_dwordx2 v[16:17], v[30:31], off offset:512
	global_store_dwordx2 v[16:17], v[32:33], off offset:1024
	global_store_dwordx2 v[16:17], v[34:35], off offset:1536
	v_lshl_add_u64 v[16:17], v[16:17], 0, s[4:5]
	s_andn2_b64 exec, exec, s[8:9]
	s_cbranch_execnz .LBB0_510

; __device__ __forceinline__ f32x4 mfma16(bf16x8 a, bf16x8 b, f32x4 c) { return __builtin_amdgcn_mfma_f32_16x16x32_bf16(a, b, c, 0, 0, 0); }
; template <class Epi>
; __device__ __forceinline__ void gemm_tile(const bf16_t* __restrict__ A, const bf16_t* __restrict__ Bt, int K, int row0, int col0, const Epi& epi, char* smem,
;                                           bool prefetched, bool nvalid, int nrow0, int ncol0) {
;     ...
;     for (int kt = 0; kt < nk; ++kt) {
;         const int cur = kt & 1;
;         if (kt + 1 < nk) GLDS_STAGE(cur ^ 1, pA, pB, kt + 1);
;         const char* cb = smem + cur * 2 * TILE_B;
; #pragma unroll
;         for (int ks = 0; ks < 2; ++ks) {
;             bf16x8 a[4], b[4];
; #pragma unroll
;             for (int m = 0; m < 4; ++m) a[m] = *(const bf16x8*)(cb + offA[m][ks]);
; #pragma unroll
;             for (int n = 0; n < 4; ++n) b[n] = *(const bf16x8*)(cb + offB[n][ks]);
; #pragma unroll
;             for (int m = 0; m < 4; ++m)
; #pragma unroll
;                 for (int n = 0; n < 4; ++n) acc[m][n] = mfma16(b[n], a[m], acc[m][n]);
;         }
;         asm volatile("s_waitcnt vmcnt(0)" ::: "memory");
;         __syncthreads();
.LBB0_563:
	v_readfirstlane_b32 s98, v110
	v_readfirstlane_b32 s99, v111
	v_readfirstlane_b32 s10, v118
	v_readfirstlane_b32 s100, v124
	v_readfirstlane_b32 s101, v125
	v_readfirstlane_b32 s17, v149
	s_nop 3
	s_sub_u32 s18, s10, s98
	s_and_b32 s98, s98, 0xffffff80
	s_and_b32 s100, s100, 0xffffff80
	s_nop 1
	v_subrev_u32_e32 v254, s98, v110
	v_subrev_u32_e32 v255, s100, v124
	s_add_i32 s13, s17, 0x8000
	s_mov_b32 m0, s13
	s_nop 0
	global_load_lds_dwordx4 v254, s[98:99]
	s_add_i32 m0, s13, 0x1000
	s_add_u32 s10, s98, s18
	s_addc_u32 s11, s99, 0
	global_load_lds_dwordx4 v254, s[10:11]
	s_add_i32 m0, s13, 0x2000
	s_add_u32 s10, s10, s18
	s_addc_u32 s11, s11, 0
	global_load_lds_dwordx4 v254, s[10:11]
	s_add_i32 m0, s13, 0x3000
	s_add_u32 s10, s10, s18
	s_addc_u32 s11, s11, 0
	global_load_lds_dwordx4 v254, s[10:11]
	s_add_u32 s98, s98, 0x80
	s_addc_u32 s99, s99, 0
	ds_read_b128 v[192:195], v85
	ds_read_b128 v[118:121], v142 offset:16384
	ds_read_b128 v[122:125], v142 offset:16896
	ds_read_b128 v[126:129], v142 offset:20480
	ds_read_b128 v[172:175], v142 offset:20992
	ds_read_b128 v[196:199], v85 offset:2048
	ds_read_b128 v[246:249], v85 offset:4096
	ds_read_b128 v[250:253], v85 offset:6144
.Lgk_loop_563:
	s_and_b32 s9, s8, 0x8000
	s_xor_b32 s12, s9, 0x8000
	v_or_b32_e32 v110, s9, v141
	v_add_u32_e32 v111, s9, v87
	s_add_i32 m0, s13, 0x4000
	s_nop 0
	s_waitcnt lgkmcnt(6)
	v_mfma_f32_16x16x32_bf16 v[0:3], v[118:121], v[192:195], v[0:3]
	global_load_lds_dwordx4 v255, s[100:101]
	ds_read_b128 v[176:179], v110 offset:16384
	s_waitcnt lgkmcnt(6)
	v_mfma_f32_16x16x32_bf16 v[4:7], v[122:125], v[192:195], v[4:7]
	ds_read_b128 v[180:183], v110 offset:16896
	s_add_i32 m0, s13, 0x5000
	s_add_u32 s10, s100, s18
	s_addc_u32 s11, s101, 0
	s_waitcnt lgkmcnt(6)
	v_mfma_f32_16x16x32_bf16 v[8:11], v[126:129], v[192:195], v[8:11]
	global_load_lds_dwordx4 v255, s[10:11]
	ds_read_b128 v[184:187], v110 offset:20480
	s_waitcnt lgkmcnt(6)
	v_mfma_f32_16x16x32_bf16 v[12:15], v[172:175], v[192:195], v[12:15]
	ds_read_b128 v[188:191], v110 offset:20992
	ds_read_b128 v[192:195], v111
	s_add_i32 m0, s13, 0x6000
	s_add_u32 s10, s10, s18
	s_addc_u32 s11, s11, 0
	s_waitcnt lgkmcnt(7)
	v_mfma_f32_16x16x32_bf16 v[16:19], v[118:121], v[196:199], v[16:19]
	global_load_lds_dwordx4 v255, s[10:11]
	v_mfma_f32_16x16x32_bf16 v[20:23], v[122:125], v[196:199], v[20:23]
	s_add_i32 m0, s13, 0x7000
	s_add_u32 s10, s10, s18
	s_addc_u32 s11, s11, 0
	v_mfma_f32_16x16x32_bf16 v[24:27], v[126:129], v[196:199], v[24:27]
	global_load_lds_dwordx4 v255, s[10:11]
	s_add_u32 s100, s100, 0x80
	s_addc_u32 s101, s101, 0
	v_mfma_f32_16x16x32_bf16 v[28:31], v[172:175], v[196:199], v[28:31]
	ds_read_b128 v[196:199], v111 offset:2048
	s_waitcnt lgkmcnt(7)
	v_mfma_f32_16x16x32_bf16 v[32:35], v[118:121], v[246:249], v[32:35]
	v_mfma_f32_16x16x32_bf16 v[36:39], v[122:125], v[246:249], v[36:39]
	v_mfma_f32_16x16x32_bf16 v[40:43], v[126:129], v[246:249], v[40:43]
	v_mfma_f32_16x16x32_bf16 v[44:47], v[172:175], v[246:249], v[44:47]
	ds_read_b128 v[246:249], v111 offset:4096
	s_waitcnt lgkmcnt(7)
	v_mfma_f32_16x16x32_bf16 v[48:51], v[118:121], v[250:253], v[48:51]
	v_mfma_f32_16x16x32_bf16 v[52:55], v[122:125], v[250:253], v[52:55]
	v_mfma_f32_16x16x32_bf16 v[56:59], v[126:129], v[250:253], v[56:59]
	v_mfma_f32_16x16x32_bf16 v[60:63], v[172:175], v[250:253], v[60:63]
	ds_read_b128 v[250:253], v111 offset:6144
	s_waitcnt lgkmcnt(3)
	v_mfma_f32_16x16x32_bf16 v[0:3], v[176:179], v[192:195], v[0:3]
	v_mfma_f32_16x16x32_bf16 v[4:7], v[180:183], v[192:195], v[4:7]
	v_mfma_f32_16x16x32_bf16 v[8:11], v[184:187], v[192:195], v[8:11]
	v_mfma_f32_16x16x32_bf16 v[12:15], v[188:191], v[192:195], v[12:15]
	s_waitcnt lgkmcnt(2)
	v_mfma_f32_16x16x32_bf16 v[16:19], v[176:179], v[196:199], v[16:19]
	v_mfma_f32_16x16x32_bf16 v[20:23], v[180:183], v[196:199], v[20:23]
	v_mfma_f32_16x16x32_bf16 v[24:27], v[184:187], v[196:199], v[24:27]
	v_mfma_f32_16x16x32_bf16 v[28:31], v[188:191], v[196:199], v[28:31]
	s_waitcnt vmcnt(0)
	s_waitcnt lgkmcnt(0)
	s_barrier
	s_add_i32 s8, s8, 0x8000
	s_cmp_eq_u32 s8, 0x78000
	s_cbranch_scc1 .Lgk_tail_563
	v_or_b32_e32 v110, s12, v142
	v_add_u32_e32 v111, s12, v85
	s_add_i32 s13, s9, s17
	ds_read_b128 v[192:195], v111
	ds_read_b128 v[118:121], v110 offset:16384
	s_mov_b32 m0, s13
	s_nop 0
	v_mfma_f32_16x16x32_bf16 v[32:35], v[176:179], v[246:249], v[32:35]
	global_load_lds_dwordx4 v254, s[98:99]
	ds_read_b128 v[122:125], v110 offset:16896
	v_mfma_f32_16x16x32_bf16 v[36:39], v[180:183], v[246:249], v[36:39]
	ds_read_b128 v[126:129], v110 offset:20480
	s_add_i32 m0, s13, 0x1000
	s_add_u32 s10, s98, s18
	s_addc_u32 s11, s99, 0
	v_mfma_f32_16x16x32_bf16 v[40:43], v[184:187], v[246:249], v[40:43]
	global_load_lds_dwordx4 v254, s[10:11]
	ds_read_b128 v[172:175], v110 offset:20992
	v_mfma_f32_16x16x32_bf16 v[44:47], v[188:191], v[246:249], v[44:47]
	ds_read_b128 v[196:199], v111 offset:2048
	ds_read_b128 v[246:249], v111 offset:4096
	s_add_i32 m0, s13, 0x2000
	s_add_u32 s10, s10, s18
	s_addc_u32 s11, s11, 0
	v_mfma_f32_16x16x32_bf16 v[48:51], v[176:179], v[250:253], v[48:51]
	global_load_lds_dwordx4 v254, s[10:11]
	v_mfma_f32_16x16x32_bf16 v[52:55], v[180:183], v[250:253], v[52:55]
	s_add_i32 m0, s13, 0x3000
	s_add_u32 s10, s10, s18
	s_addc_u32 s11, s11, 0
	v_mfma_f32_16x16x32_bf16 v[56:59], v[184:187], v[250:253], v[56:59]
	global_load_lds_dwordx4 v254, s[10:11]
	s_add_u32 s98, s98, 0x80
	s_addc_u32 s99, s99, 0
	v_mfma_f32_16x16x32_bf16 v[60:63], v[188:191], v[250:253], v[60:63]
	ds_read_b128 v[250:253], v111 offset:6144
	s_branch .Lgk_loop_563

; __device__ __forceinline__ f32x4 mfma16(bf16x8 a, bf16x8 b, f32x4 c) { return __builtin_amdgcn_mfma_f32_16x16x32_bf16(a, b, c, 0, 0, 0); }
; template <class Epi>
; __device__ __forceinline__ void gemm_tile(const bf16_t* __restrict__ A, const bf16_t* __restrict__ Bt, int K, int row0, int col0, const Epi& epi, char* smem,
;                                           bool prefetched, bool nvalid, int nrow0, int ncol0) {
;     ...
;     for (int kt = 0; kt < nk; ++kt) {
;         const int cur = kt & 1;
;         if (kt + 1 < nk) GLDS_STAGE(cur ^ 1, pA, pB, kt + 1);
;         const char* cb = smem + cur * 2 * TILE_B;
; #pragma unroll
;         for (int ks = 0; ks < 2; ++ks) {
;             bf16x8 a[4], b[4];
; #pragma unroll
;             for (int m = 0; m < 4; ++m) a[m] = *(const bf16x8*)(cb + offA[m][ks]);
; #pragma unroll
;             for (int n = 0; n < 4; ++n) b[n] = *(const bf16x8*)(cb + offB[n][ks]);
; #pragma unroll
;             for (int m = 0; m < 4; ++m)
; #pragma unroll
;                 for (int n = 0; n < 4; ++n) acc[m][n] = mfma16(b[n], a[m], acc[m][n]);
;         }
;         asm volatile("s_waitcnt vmcnt(0)" ::: "memory");
;         __syncthreads();
.LBB0_619:
	v_readfirstlane_b32 s98, v92
	v_readfirstlane_b32 s99, v93
	v_readfirstlane_b32 s8, v94
	v_readfirstlane_b32 s100, v100
	v_readfirstlane_b32 s101, v101
	v_readfirstlane_b32 s12, v149
	s_nop 3
	s_sub_u32 s13, s8, s98
	s_and_b32 s98, s98, 0xffffff80
	s_and_b32 s100, s100, 0xffffff80
	s_nop 1
	v_subrev_u32_e32 v254, s98, v92
	v_subrev_u32_e32 v255, s100, v100
	s_add_i32 s11, s12, 0x8000
	s_mov_b32 m0, s11
	s_nop 0
	global_load_lds_dwordx4 v254, s[98:99]
	s_add_i32 m0, s11, 0x1000
	s_add_u32 s8, s98, s13
	s_addc_u32 s9, s99, 0
	global_load_lds_dwordx4 v254, s[8:9]
	s_add_i32 m0, s11, 0x2000
	s_add_u32 s8, s8, s13
	s_addc_u32 s9, s9, 0
	global_load_lds_dwordx4 v254, s[8:9]
	s_add_i32 m0, s11, 0x3000
	s_add_u32 s8, s8, s13
	s_addc_u32 s9, s9, 0
	global_load_lds_dwordx4 v254, s[8:9]
	s_add_u32 s98, s98, 0x80
	s_addc_u32 s99, s99, 0
	ds_read_b128 v[174:177], v108
	ds_read_b128 v[92:95], v110 offset:16384
	ds_read_b128 v[96:99], v110 offset:16896
	ds_read_b128 v[100:103], v110 offset:20480
	ds_read_b128 v[104:107], v110 offset:20992
	ds_read_b128 v[178:181], v108 offset:2048
	ds_read_b128 v[246:249], v108 offset:4096
	ds_read_b128 v[250:253], v108 offset:6144
.Lgk_loop_619:
	s_and_b32 s3, s1, 0x8000
	s_xor_b32 s10, s3, 0x8000
	v_or_b32_e32 v129, s3, v111
	v_add_u32_e32 v130, s3, v109
	s_add_i32 m0, s11, 0x4000
	s_nop 0
	s_waitcnt lgkmcnt(6)
	v_mfma_f32_16x16x32_bf16 v[0:3], v[92:95], v[174:177], v[0:3]
	global_load_lds_dwordx4 v255, s[100:101]
	ds_read_b128 v[142:145], v129 offset:16384
	s_waitcnt lgkmcnt(6)
	v_mfma_f32_16x16x32_bf16 v[4:7], v[96:99], v[174:177], v[4:7]
	ds_read_b128 v[162:165], v129 offset:16896
	s_add_i32 m0, s11, 0x5000
	s_add_u32 s8, s100, s13
	s_addc_u32 s9, s101, 0
	s_waitcnt lgkmcnt(6)
	v_mfma_f32_16x16x32_bf16 v[8:11], v[100:103], v[174:177], v[8:11]
	global_load_lds_dwordx4 v255, s[8:9]
	ds_read_b128 v[166:169], v129 offset:20480
	s_waitcnt lgkmcnt(6)
	v_mfma_f32_16x16x32_bf16 v[12:15], v[104:107], v[174:177], v[12:15]
	ds_read_b128 v[170:173], v129 offset:20992
	ds_read_b128 v[174:177], v130
	s_add_i32 m0, s11, 0x6000
	s_add_u32 s8, s8, s13
	s_addc_u32 s9, s9, 0
	s_waitcnt lgkmcnt(7)
	v_mfma_f32_16x16x32_bf16 v[16:19], v[92:95], v[178:181], v[16:19]
	global_load_lds_dwordx4 v255, s[8:9]
	v_mfma_f32_16x16x32_bf16 v[20:23], v[96:99], v[178:181], v[20:23]
	s_add_i32 m0, s11, 0x7000
	s_add_u32 s8, s8, s13
	s_addc_u32 s9, s9, 0
	v_mfma_f32_16x16x32_bf16 v[24:27], v[100:103], v[178:181], v[24:27]
	global_load_lds_dwordx4 v255, s[8:9]
	s_add_u32 s100, s100, 0x80
	s_addc_u32 s101, s101, 0
	v_mfma_f32_16x16x32_bf16 v[28:31], v[104:107], v[178:181], v[28:31]
	ds_read_b128 v[178:181], v130 offset:2048
	s_waitcnt lgkmcnt(7)
	v_mfma_f32_16x16x32_bf16 v[32:35], v[92:95], v[246:249], v[32:35]
	v_mfma_f32_16x16x32_bf16 v[36:39], v[96:99], v[246:249], v[36:39]
	v_mfma_f32_16x16x32_bf16 v[40:43], v[100:103], v[246:249], v[40:43]
	v_mfma_f32_16x16x32_bf16 v[44:47], v[104:107], v[246:249], v[44:47]
	ds_read_b128 v[246:249], v130 offset:4096
	s_waitcnt lgkmcnt(7)
	v_mfma_f32_16x16x32_bf16 v[48:51], v[92:95], v[250:253], v[48:51]
	v_mfma_f32_16x16x32_bf16 v[52:55], v[96:99], v[250:253], v[52:55]
	v_mfma_f32_16x16x32_bf16 v[56:59], v[100:103], v[250:253], v[56:59]
	v_mfma_f32_16x16x32_bf16 v[60:63], v[104:107], v[250:253], v[60:63]
	ds_read_b128 v[250:253], v130 offset:6144
	s_waitcnt lgkmcnt(3)
	v_mfma_f32_16x16x32_bf16 v[0:3], v[142:145], v[174:177], v[0:3]
	v_mfma_f32_16x16x32_bf16 v[4:7], v[162:165], v[174:177], v[4:7]
	v_mfma_f32_16x16x32_bf16 v[8:11], v[166:169], v[174:177], v[8:11]
	v_mfma_f32_16x16x32_bf16 v[12:15], v[170:173], v[174:177], v[12:15]
	s_waitcnt lgkmcnt(2)
	v_mfma_f32_16x16x32_bf16 v[16:19], v[142:145], v[178:181], v[16:19]
	v_mfma_f32_16x16x32_bf16 v[20:23], v[162:165], v[178:181], v[20:23]
	v_mfma_f32_16x16x32_bf16 v[24:27], v[166:169], v[178:181], v[24:27]
	v_mfma_f32_16x16x32_bf16 v[28:31], v[170:173], v[178:181], v[28:31]
	s_waitcnt vmcnt(0)
	s_waitcnt lgkmcnt(0)
	s_barrier
	s_add_i32 s1, s1, 0x8000
	s_cmp_eq_u32 s1, 0x1f8000
	s_cbranch_scc1 .Lgk_tail_619
	v_or_b32_e32 v129, s10, v110
	v_add_u32_e32 v130, s10, v108
	s_add_i32 s11, s3, s12
	ds_read_b128 v[174:177], v130
	ds_read_b128 v[92:95], v129 offset:16384
	s_mov_b32 m0, s11
	s_nop 0
	v_mfma_f32_16x16x32_bf16 v[32:35], v[142:145], v[246:249], v[32:35]
	global_load_lds_dwordx4 v254, s[98:99]
	ds_read_b128 v[96:99], v129 offset:16896
	v_mfma_f32_16x16x32_bf16 v[36:39], v[162:165], v[246:249], v[36:39]
	ds_read_b128 v[100:103], v129 offset:20480
	s_add_i32 m0, s11, 0x1000
	s_add_u32 s8, s98, s13
	s_addc_u32 s9, s99, 0
	v_mfma_f32_16x16x32_bf16 v[40:43], v[166:169], v[246:249], v[40:43]
	global_load_lds_dwordx4 v254, s[8:9]
	ds_read_b128 v[104:107], v129 offset:20992
	v_mfma_f32_16x16x32_bf16 v[44:47], v[170:173], v[246:249], v[44:47]
	ds_read_b128 v[178:181], v130 offset:2048
	ds_read_b128 v[246:249], v130 offset:4096
	s_add_i32 m0, s11, 0x2000
	s_add_u32 s8, s8, s13
	s_addc_u32 s9, s9, 0
	v_mfma_f32_16x16x32_bf16 v[48:51], v[142:145], v[250:253], v[48:51]
	global_load_lds_dwordx4 v254, s[8:9]
	v_mfma_f32_16x16x32_bf16 v[52:55], v[162:165], v[250:253], v[52:55]
	s_add_i32 m0, s11, 0x3000
	s_add_u32 s8, s8, s13
	s_addc_u32 s9, s9, 0
	v_mfma_f32_16x16x32_bf16 v[56:59], v[166:169], v[250:253], v[56:59]
	global_load_lds_dwordx4 v254, s[8:9]
	s_add_u32 s98, s98, 0x80
	s_addc_u32 s99, s99, 0
	v_mfma_f32_16x16x32_bf16 v[60:63], v[170:173], v[250:253], v[60:63]
	ds_read_b128 v[250:253], v130 offset:6144
	s_branch .Lgk_loop_619

; __device__ __forceinline__ u32x2 pack4(f32x4 v) { u32x2 r; r.x = cvt_pk_bf16(v[0], v[1]); r.y = cvt_pk_bf16(v[2], v[3]); return r; }
; __device__ __forceinline__ void rmsnorm_phase(const float* x, const float* g, bf16_t* outb, float* outf) {
;     ...
;     for (int row = gw; row < T; row += nw) {
;         const float* xr = x + (size_t)row * D;
;         f32x4 v[4];
;         float ss = 0.f;
; #pragma unroll
;         for (int i = 0; i < 4; ++i) { v[i] = __builtin_nontemporal_load((const f32x4*)(xr + (lane + i * 64) * 4)); ss += v[i][0] * v[i][0] + v[i][1] * v[i][1] + v[i][2] * v[i][2] + v[i][3] * v[i][3]; }
; #pragma unroll
;         for (int o = 32; o >= 1; o >>= 1) ss += __shfl_xor(ss, o);
;         const float r = rsqrtf(ss * (1.0f / D) + EPS);
; #pragma unroll
;         for (int i = 0; i < 4; ++i) {
;             const f32x4 y = v[i] * r * gv[i];
;             if (outb) *(u32x2*)(outb + (size_t)row * D + (lane + i * 64) * 4) = pack4(y);
;             else __builtin_nontemporal_store(y, (f32x4*)(outf + (size_t)row * D + (lane + i * 64) * 4));
;         }
;     }
.LBB0_669:
	global_load_dwordx4 v[28:31], v[18:19], off offset:-3072 nt
	global_load_dwordx4 v[32:35], v[18:19], off offset:-2048 nt
	global_load_dwordx4 v[36:39], v[18:19], off offset:-1024 nt
	global_load_dwordx4 v[40:43], v[18:19], off nt
	v_add_u32_e32 v27, s40, v27
	v_cmp_lt_i32_e32 vcc, s11, v27
	s_or_b64 s[8:9], vcc, s[8:9]
	v_lshl_add_u64 v[18:19], v[18:19], 0, s[6:7]
	s_waitcnt vmcnt(0)
	v_mov_b32_e32 v46, v29
	v_mov_b32_e32 v47, v33
	v_mov_b32_e32 v44, v28
	v_mov_b32_e32 v45, v32
	v_mov_b32_e32 v54, v37
	v_mov_b32_e32 v55, v41
	v_pk_mul_f32 v[46:47], v[46:47], v[46:47]
	v_mov_b32_e32 v48, v30
	v_mov_b32_e32 v49, v34
	v_mov_b32_e32 v52, v36
	v_mov_b32_e32 v53, v40
	v_pk_mul_f32 v[54:55], v[54:55], v[54:55]
	v_pk_fma_f32 v[44:45], v[44:45], v[44:45], v[46:47]
	v_mov_b32_e32 v50, v31
	v_mov_b32_e32 v51, v35
	v_mov_b32_e32 v56, v38
	v_mov_b32_e32 v57, v42
	v_pk_fma_f32 v[46:47], v[52:53], v[52:53], v[54:55]
	v_pk_fma_f32 v[44:45], v[48:49], v[48:49], v[44:45]
	v_mov_b32_e32 v58, v39
	v_mov_b32_e32 v59, v43
	v_pk_fma_f32 v[46:47], v[56:57], v[56:57], v[46:47]
	v_pk_fma_f32 v[44:45], v[50:51], v[50:51], v[44:45]
	v_pk_fma_f32 v[46:47], v[58:59], v[58:59], v[46:47]
	v_add_f32_e32 v44, v44, v45
	v_add_f32_e32 v44, v44, v46
	v_add_f32_e32 v44, v44, v47
	v_mov_b32_e32 v45, v44
	s_nop 1
	v_permlane32_swap_b32_e32 v44, v45
	v_add_f32_e32 v44, v44, v45
	v_mov_b32_e32 v45, v44
	s_nop 1
	v_permlane16_swap_b32_e32 v44, v45
	v_add_f32_e32 v44, v44, v45
	s_nop 1
	v_add_f32_dpp v44, v44, v44 row_ror:8 row_mask:0xf bank_mask:0xf
	s_nop 1
	v_add_f32_dpp v44, v44, v44 row_ror:4 row_mask:0xf bank_mask:0xf
	s_nop 1
	v_add_f32_dpp v44, v44, v44 quad_perm:[2,3,0,1] row_mask:0xf bank_mask:0xf
	s_nop 1
	v_add_f32_dpp v44, v44, v44 quad_perm:[1,0,3,2] row_mask:0xf bank_mask:0xf
	v_fmamk_f32 v44, v44, 0x3a800000, v26
	v_mul_f32_e32 v45, 0x4b800000, v44
	v_cmp_gt_f32_e32 vcc, s10, v44
	s_nop 1
	v_cndmask_b32_e32 v44, v44, v45, vcc
	v_rsq_f32_e32 v44, v44
	s_nop 0
	v_mul_f32_e32 v45, 0x45800000, v44
	v_cndmask_b32_e32 v44, v44, v45, vcc
	v_pk_mul_f32 v[28:29], v[28:29], v[44:45] op_sel_hi:[1,0]
	v_pk_mul_f32 v[30:31], v[30:31], v[44:45] op_sel_hi:[1,0]
	v_pk_mul_f32 v[32:33], v[32:33], v[44:45] op_sel_hi:[1,0]
	v_pk_mul_f32 v[34:35], v[34:35], v[44:45] op_sel_hi:[1,0]
	v_pk_mul_f32 v[36:37], v[36:37], v[44:45] op_sel_hi:[1,0]
	v_pk_mul_f32 v[38:39], v[38:39], v[44:45] op_sel_hi:[1,0]
	v_pk_mul_f32 v[40:41], v[40:41], v[44:45] op_sel_hi:[1,0]
	v_pk_mul_f32 v[42:43], v[42:43], v[44:45] op_sel_hi:[1,0]
	v_pk_mul_f32 v[30:31], v[10:11], v[30:31]
	v_pk_mul_f32 v[28:29], v[8:9], v[28:29]
	v_pk_mul_f32 v[34:35], v[2:3], v[34:35]
	v_pk_mul_f32 v[32:33], v[0:1], v[32:33]
	v_pk_mul_f32 v[38:39], v[6:7], v[38:39]
	v_pk_mul_f32 v[36:37], v[4:5], v[36:37]
	v_pk_mul_f32 v[42:43], v[14:15], v[42:43]
	v_pk_mul_f32 v[40:41], v[12:13], v[40:41]
	v_cvt_pk_bf16_f32 v28, v28, v29
	v_cvt_pk_bf16_f32 v29, v30, v31
	v_cvt_pk_bf16_f32 v30, v32, v33
	v_cvt_pk_bf16_f32 v31, v34, v35
	v_cvt_pk_bf16_f32 v32, v36, v37
	v_cvt_pk_bf16_f32 v33, v38, v39
	v_cvt_pk_bf16_f32 v34, v40, v41
	v_cvt_pk_bf16_f32 v35, v42, v43
	global_store_dwordx2 v[16:17], v[28:29], off
	global_store_dwordx2 v[16:17], v[30:31], off offset:512
	global_store_dwordx2 v[16:17], v[32:33], off offset:1024
	global_store_dwordx2 v[16:17], v[34:35], off offset:1536
	v_lshl_add_u64 v[16:17], v[16:17], 0, s[2:3]
	s_andn2_b64 exec, exec, s[8:9]
	s_cbranch_execnz .LBB0_669

; __device__ __forceinline__ f32x4 mfma16(bf16x8 a, bf16x8 b, f32x4 c) { return __builtin_amdgcn_mfma_f32_16x16x32_bf16(a, b, c, 0, 0, 0); }
; template <class Epi>
; __device__ __forceinline__ void gemm_tile(const bf16_t* __restrict__ A, const bf16_t* __restrict__ Bt, int K, int row0, int col0, const Epi& epi, char* smem,
;                                           bool prefetched, bool nvalid, int nrow0, int ncol0) {
;     ...
;     for (int kt = 0; kt < nk; ++kt) {
;         const int cur = kt & 1;
;         if (kt + 1 < nk) GLDS_STAGE(cur ^ 1, pA, pB, kt + 1);
;         const char* cb = smem + cur * 2 * TILE_B;
; #pragma unroll
;         for (int ks = 0; ks < 2; ++ks) {
;             bf16x8 a[4], b[4];
; #pragma unroll
;             for (int m = 0; m < 4; ++m) a[m] = *(const bf16x8*)(cb + offA[m][ks]);
; #pragma unroll
;             for (int n = 0; n < 4; ++n) b[n] = *(const bf16x8*)(cb + offB[n][ks]);
; #pragma unroll
;             for (int m = 0; m < 4; ++m)
; #pragma unroll
;                 for (int n = 0; n < 4; ++n) acc[m][n] = mfma16(b[n], a[m], acc[m][n]);
;         }
;         asm volatile("s_waitcnt vmcnt(0)" ::: "memory");
;         __syncthreads();
.LBB0_723:
	v_readfirstlane_b32 s98, v64
	v_readfirstlane_b32 s99, v65
	v_readfirstlane_b32 s12, v66
	v_readfirstlane_b32 s100, v72
	v_readfirstlane_b32 s101, v73
	v_readfirstlane_b32 s15, v149
	s_nop 3
	s_sub_u32 s16, s12, s98
	s_and_b32 s98, s98, 0xffffff80
	s_and_b32 s100, s100, 0xffffff80
	s_nop 1
	v_subrev_u32_e32 v254, s98, v64
	v_subrev_u32_e32 v255, s100, v72
	s_add_i32 s14, s15, 0x8000
	s_mov_b32 m0, s14
	s_nop 0
	global_load_lds_dwordx4 v254, s[98:99]
	s_add_i32 m0, s14, 0x1000
	s_add_u32 s12, s98, s16
	s_addc_u32 s13, s99, 0
	global_load_lds_dwordx4 v254, s[12:13]
	s_add_i32 m0, s14, 0x2000
	s_add_u32 s12, s12, s16
	s_addc_u32 s13, s13, 0
	global_load_lds_dwordx4 v254, s[12:13]
	s_add_i32 m0, s14, 0x3000
	s_add_u32 s12, s12, s16
	s_addc_u32 s13, s13, 0
	global_load_lds_dwordx4 v254, s[12:13]
	s_add_u32 s98, s98, 0x80
	s_addc_u32 s99, s99, 0
	ds_read_b128 v[188:191], v137
	ds_read_b128 v[64:67], v143 offset:16384
	ds_read_b128 v[68:71], v143 offset:16896
	ds_read_b128 v[72:75], v143 offset:20480
	ds_read_b128 v[76:79], v143 offset:20992
	ds_read_b128 v[192:195], v137 offset:2048
	ds_read_b128 v[246:249], v137 offset:4096
	ds_read_b128 v[250:253], v137 offset:6144
.Lgk_loop_723:
	s_and_b32 s10, s7, 0x8000
	s_xor_b32 s11, s10, 0x8000
	v_or_b32_e32 v179, s10, v142
	v_add_u32_e32 v196, s10, v141
	s_add_i32 m0, s14, 0x4000
	s_nop 0
	s_waitcnt lgkmcnt(6)
	v_mfma_f32_16x16x32_bf16 v[0:3], v[64:67], v[188:191], v[0:3]
	global_load_lds_dwordx4 v255, s[100:101]
	ds_read_b128 v[80:83], v179 offset:16384
	s_waitcnt lgkmcnt(6)
	v_mfma_f32_16x16x32_bf16 v[4:7], v[68:71], v[188:191], v[4:7]
	ds_read_b128 v[128:131], v179 offset:16896
	s_add_i32 m0, s14, 0x5000
	s_add_u32 s12, s100, s16
	s_addc_u32 s13, s101, 0
	s_waitcnt lgkmcnt(6)
	v_mfma_f32_16x16x32_bf16 v[8:11], v[72:75], v[188:191], v[8:11]
	global_load_lds_dwordx4 v255, s[12:13]
	ds_read_b128 v[180:183], v179 offset:20480
	s_waitcnt lgkmcnt(6)
	v_mfma_f32_16x16x32_bf16 v[12:15], v[76:79], v[188:191], v[12:15]
	ds_read_b128 v[184:187], v179 offset:20992
	ds_read_b128 v[188:191], v196
	s_add_i32 m0, s14, 0x6000
	s_add_u32 s12, s12, s16
	s_addc_u32 s13, s13, 0
	s_waitcnt lgkmcnt(7)
	v_mfma_f32_16x16x32_bf16 v[16:19], v[64:67], v[192:195], v[16:19]
	global_load_lds_dwordx4 v255, s[12:13]
	v_mfma_f32_16x16x32_bf16 v[20:23], v[68:71], v[192:195], v[20:23]
	s_add_i32 m0, s14, 0x7000
	s_add_u32 s12, s12, s16
	s_addc_u32 s13, s13, 0
	v_mfma_f32_16x16x32_bf16 v[24:27], v[72:75], v[192:195], v[24:27]
	global_load_lds_dwordx4 v255, s[12:13]
	s_add_u32 s100, s100, 0x80
	s_addc_u32 s101, s101, 0
	v_mfma_f32_16x16x32_bf16 v[28:31], v[76:79], v[192:195], v[28:31]
	ds_read_b128 v[192:195], v196 offset:2048
	s_waitcnt lgkmcnt(7)
	v_mfma_f32_16x16x32_bf16 v[32:35], v[64:67], v[246:249], v[32:35]
	v_mfma_f32_16x16x32_bf16 v[36:39], v[68:71], v[246:249], v[36:39]
	v_mfma_f32_16x16x32_bf16 v[40:43], v[72:75], v[246:249], v[40:43]
	v_mfma_f32_16x16x32_bf16 v[44:47], v[76:79], v[246:249], v[44:47]
	ds_read_b128 v[246:249], v196 offset:4096
	s_waitcnt lgkmcnt(7)
	v_mfma_f32_16x16x32_bf16 v[48:51], v[64:67], v[250:253], v[48:51]
	v_mfma_f32_16x16x32_bf16 v[52:55], v[68:71], v[250:253], v[52:55]
	v_mfma_f32_16x16x32_bf16 v[56:59], v[72:75], v[250:253], v[56:59]
	v_mfma_f32_16x16x32_bf16 v[60:63], v[76:79], v[250:253], v[60:63]
	ds_read_b128 v[250:253], v196 offset:6144
	s_waitcnt lgkmcnt(3)
	v_mfma_f32_16x16x32_bf16 v[0:3], v[80:83], v[188:191], v[0:3]
	v_mfma_f32_16x16x32_bf16 v[4:7], v[128:131], v[188:191], v[4:7]
	v_mfma_f32_16x16x32_bf16 v[8:11], v[180:183], v[188:191], v[8:11]
	v_mfma_f32_16x16x32_bf16 v[12:15], v[184:187], v[188:191], v[12:15]
	s_waitcnt lgkmcnt(2)
	v_mfma_f32_16x16x32_bf16 v[16:19], v[80:83], v[192:195], v[16:19]
	v_mfma_f32_16x16x32_bf16 v[20:23], v[128:131], v[192:195], v[20:23]
	v_mfma_f32_16x16x32_bf16 v[24:27], v[180:183], v[192:195], v[24:27]
	v_mfma_f32_16x16x32_bf16 v[28:31], v[184:187], v[192:195], v[28:31]
	s_waitcnt vmcnt(0)
	s_waitcnt lgkmcnt(0)
	s_barrier
	s_add_i32 s7, s7, 0x8000
	s_cmp_eq_u32 s7, 0x78000
	s_cbranch_scc1 .Lgk_tail_723
	v_or_b32_e32 v179, s11, v143
	v_add_u32_e32 v196, s11, v137
	s_add_i32 s14, s10, s15
	ds_read_b128 v[188:191], v196
	ds_read_b128 v[64:67], v179 offset:16384
	s_mov_b32 m0, s14
	s_nop 0
	v_mfma_f32_16x16x32_bf16 v[32:35], v[80:83], v[246:249], v[32:35]
	global_load_lds_dwordx4 v254, s[98:99]
	ds_read_b128 v[68:71], v179 offset:16896
	v_mfma_f32_16x16x32_bf16 v[36:39], v[128:131], v[246:249], v[36:39]
	ds_read_b128 v[72:75], v179 offset:20480
	s_add_i32 m0, s14, 0x1000
	s_add_u32 s12, s98, s16
	s_addc_u32 s13, s99, 0
	v_mfma_f32_16x16x32_bf16 v[40:43], v[180:183], v[246:249], v[40:43]
	global_load_lds_dwordx4 v254, s[12:13]
	ds_read_b128 v[76:79], v179 offset:20992
	v_mfma_f32_16x16x32_bf16 v[44:47], v[184:187], v[246:249], v[44:47]
	ds_read_b128 v[192:195], v196 offset:2048
	ds_read_b128 v[246:249], v196 offset:4096
	s_add_i32 m0, s14, 0x2000
	s_add_u32 s12, s12, s16
	s_addc_u32 s13, s13, 0
	v_mfma_f32_16x16x32_bf16 v[48:51], v[80:83], v[250:253], v[48:51]
	global_load_lds_dwordx4 v254, s[12:13]
	v_mfma_f32_16x16x32_bf16 v[52:55], v[128:131], v[250:253], v[52:55]
	s_add_i32 m0, s14, 0x3000
	s_add_u32 s12, s12, s16
	s_addc_u32 s13, s13, 0
	v_mfma_f32_16x16x32_bf16 v[56:59], v[180:183], v[250:253], v[56:59]
	global_load_lds_dwordx4 v254, s[12:13]
	s_add_u32 s98, s98, 0x80
	s_addc_u32 s99, s99, 0
	v_mfma_f32_16x16x32_bf16 v[60:63], v[184:187], v[250:253], v[60:63]
	ds_read_b128 v[250:253], v196 offset:6144
	s_branch .Lgk_loop_723

; __device__ __forceinline__ f32x4 mfma16(bf16x8 a, bf16x8 b, f32x4 c) { return __builtin_amdgcn_mfma_f32_16x16x32_bf16(a, b, c, 0, 0, 0); }
; template <class Epi>
; __device__ __forceinline__ void gemm_tile(const bf16_t* __restrict__ A, const bf16_t* __restrict__ Bt, int K, int row0, int col0, const Epi& epi, char* smem,
;                                           bool prefetched, bool nvalid, int nrow0, int ncol0) {
;     ...
;     for (int kt = 0; kt < nk; ++kt) {
;         const int cur = kt & 1;
;         if (kt + 1 < nk) GLDS_STAGE(cur ^ 1, pA, pB, kt + 1);
;         const char* cb = smem + cur * 2 * TILE_B;
; #pragma unroll
;         for (int ks = 0; ks < 2; ++ks) {
;             bf16x8 a[4], b[4];
; #pragma unroll
;             for (int m = 0; m < 4; ++m) a[m] = *(const bf16x8*)(cb + offA[m][ks]);
; #pragma unroll
;             for (int n = 0; n < 4; ++n) b[n] = *(const bf16x8*)(cb + offB[n][ks]);
; #pragma unroll
;             for (int m = 0; m < 4; ++m)
; #pragma unroll
;                 for (int n = 0; n < 4; ++n) acc[m][n] = mfma16(b[n], a[m], acc[m][n]);
;         }
;         asm volatile("s_waitcnt vmcnt(0)" ::: "memory");
;         __syncthreads();
.LBB0_766:
	v_readfirstlane_b32 s98, v106
	v_readfirstlane_b32 s99, v107
	v_readfirstlane_b32 s10, v108
	v_readfirstlane_b32 s100, v120
	v_readfirstlane_b32 s101, v121
	v_readfirstlane_b32 s13, v149
	s_nop 3
	s_sub_u32 s16, s10, s98
	s_and_b32 s98, s98, 0xffffff80
	s_and_b32 s100, s100, 0xffffff80
	s_nop 1
	v_subrev_u32_e32 v254, s98, v106
	v_subrev_u32_e32 v255, s100, v120
	s_add_i32 s12, s13, 0x8000
	s_mov_b32 m0, s12
	s_nop 0
	global_load_lds_dwordx4 v254, s[98:99]
	s_add_i32 m0, s12, 0x1000
	s_add_u32 s10, s98, s16
	s_addc_u32 s11, s99, 0
	global_load_lds_dwordx4 v254, s[10:11]
	s_add_i32 m0, s12, 0x2000
	s_add_u32 s10, s10, s16
	s_addc_u32 s11, s11, 0
	global_load_lds_dwordx4 v254, s[10:11]
	s_add_i32 m0, s12, 0x3000
	s_add_u32 s10, s10, s16
	s_addc_u32 s11, s11, 0
	global_load_lds_dwordx4 v254, s[10:11]
	s_add_u32 s98, s98, 0x80
	s_addc_u32 s99, s99, 0
	ds_read_b128 v[190:193], v128
	ds_read_b128 v[106:109], v131 offset:16384
	ds_read_b128 v[118:121], v131 offset:16896
	ds_read_b128 v[122:125], v131 offset:20480
	ds_read_b128 v[170:173], v131 offset:20992
	ds_read_b128 v[194:197], v128 offset:2048
	ds_read_b128 v[198:201], v128 offset:4096
	ds_read_b128 v[246:249], v128 offset:6144
.Lgk_loop_766:
	s_and_b32 s8, s1, 0x8000
	s_xor_b32 s9, s8, 0x8000
	v_or_b32_e32 v164, s8, v130
	v_add_u32_e32 v165, s8, v129
	s_add_i32 m0, s12, 0x4000
	s_nop 0
	s_waitcnt lgkmcnt(6)
	v_mfma_f32_16x16x32_bf16 v[0:3], v[106:109], v[190:193], v[0:3]
	global_load_lds_dwordx4 v255, s[100:101]
	ds_read_b128 v[174:177], v164 offset:16384
	s_waitcnt lgkmcnt(6)
	v_mfma_f32_16x16x32_bf16 v[4:7], v[118:121], v[190:193], v[4:7]
	ds_read_b128 v[178:181], v164 offset:16896
	s_add_i32 m0, s12, 0x5000
	s_add_u32 s10, s100, s16
	s_addc_u32 s11, s101, 0
	s_waitcnt lgkmcnt(6)
	v_mfma_f32_16x16x32_bf16 v[8:11], v[122:125], v[190:193], v[8:11]
	global_load_lds_dwordx4 v255, s[10:11]
	ds_read_b128 v[182:185], v164 offset:20480
	s_waitcnt lgkmcnt(6)
	v_mfma_f32_16x16x32_bf16 v[12:15], v[170:173], v[190:193], v[12:15]
	ds_read_b128 v[186:189], v164 offset:20992
	ds_read_b128 v[190:193], v165
	s_add_i32 m0, s12, 0x6000
	s_add_u32 s10, s10, s16
	s_addc_u32 s11, s11, 0
	s_waitcnt lgkmcnt(7)
	v_mfma_f32_16x16x32_bf16 v[16:19], v[106:109], v[194:197], v[16:19]
	global_load_lds_dwordx4 v255, s[10:11]
	v_mfma_f32_16x16x32_bf16 v[20:23], v[118:121], v[194:197], v[20:23]
	s_add_i32 m0, s12, 0x7000
	s_add_u32 s10, s10, s16
	s_addc_u32 s11, s11, 0
	v_mfma_f32_16x16x32_bf16 v[24:27], v[122:125], v[194:197], v[24:27]
	global_load_lds_dwordx4 v255, s[10:11]
	s_add_u32 s100, s100, 0x80
	s_addc_u32 s101, s101, 0
	v_mfma_f32_16x16x32_bf16 v[28:31], v[170:173], v[194:197], v[28:31]
	ds_read_b128 v[194:197], v165 offset:2048
	s_waitcnt lgkmcnt(7)
	v_mfma_f32_16x16x32_bf16 v[32:35], v[106:109], v[198:201], v[32:35]
	v_mfma_f32_16x16x32_bf16 v[36:39], v[118:121], v[198:201], v[36:39]
	v_mfma_f32_16x16x32_bf16 v[40:43], v[122:125], v[198:201], v[40:43]
	v_mfma_f32_16x16x32_bf16 v[44:47], v[170:173], v[198:201], v[44:47]
	ds_read_b128 v[198:201], v165 offset:4096
	s_waitcnt lgkmcnt(7)
	v_mfma_f32_16x16x32_bf16 v[48:51], v[106:109], v[246:249], v[48:51]
	v_mfma_f32_16x16x32_bf16 v[52:55], v[118:121], v[246:249], v[52:55]
	v_mfma_f32_16x16x32_bf16 v[56:59], v[122:125], v[246:249], v[56:59]
	v_mfma_f32_16x16x32_bf16 v[60:63], v[170:173], v[246:249], v[60:63]
	ds_read_b128 v[246:249], v165 offset:6144
	s_waitcnt lgkmcnt(3)
	v_mfma_f32_16x16x32_bf16 v[0:3], v[174:177], v[190:193], v[0:3]
	v_mfma_f32_16x16x32_bf16 v[4:7], v[178:181], v[190:193], v[4:7]
	v_mfma_f32_16x16x32_bf16 v[8:11], v[182:185], v[190:193], v[8:11]
	v_mfma_f32_16x16x32_bf16 v[12:15], v[186:189], v[190:193], v[12:15]
	s_waitcnt lgkmcnt(2)
	v_mfma_f32_16x16x32_bf16 v[16:19], v[174:177], v[194:197], v[16:19]
	v_mfma_f32_16x16x32_bf16 v[20:23], v[178:181], v[194:197], v[20:23]
	v_mfma_f32_16x16x32_bf16 v[24:27], v[182:185], v[194:197], v[24:27]
	v_mfma_f32_16x16x32_bf16 v[28:31], v[186:189], v[194:197], v[28:31]
	s_waitcnt vmcnt(0)
	s_waitcnt lgkmcnt(0)
	s_barrier
	s_add_i32 s1, s1, 0x8000
	s_cmp_eq_u32 s1, 0x78000
	s_cbranch_scc1 .Lgk_tail_766
	v_or_b32_e32 v164, s9, v131
	v_add_u32_e32 v165, s9, v128
	s_add_i32 s12, s8, s13
	ds_read_b128 v[190:193], v165
	ds_read_b128 v[106:109], v164 offset:16384
	s_mov_b32 m0, s12
	s_nop 0
	v_mfma_f32_16x16x32_bf16 v[32:35], v[174:177], v[198:201], v[32:35]
	global_load_lds_dwordx4 v254, s[98:99]
	ds_read_b128 v[118:121], v164 offset:16896
	v_mfma_f32_16x16x32_bf16 v[36:39], v[178:181], v[198:201], v[36:39]
	ds_read_b128 v[122:125], v164 offset:20480
	s_add_i32 m0, s12, 0x1000
	s_add_u32 s10, s98, s16
	s_addc_u32 s11, s99, 0
	v_mfma_f32_16x16x32_bf16 v[40:43], v[182:185], v[198:201], v[40:43]
	global_load_lds_dwordx4 v254, s[10:11]
	ds_read_b128 v[170:173], v164 offset:20992
	v_mfma_f32_16x16x32_bf16 v[44:47], v[186:189], v[198:201], v[44:47]
	ds_read_b128 v[194:197], v165 offset:2048
	ds_read_b128 v[198:201], v165 offset:4096
	s_add_i32 m0, s12, 0x2000
	s_add_u32 s10, s10, s16
	s_addc_u32 s11, s11, 0
	v_mfma_f32_16x16x32_bf16 v[48:51], v[174:177], v[246:249], v[48:51]
	global_load_lds_dwordx4 v254, s[10:11]
	v_mfma_f32_16x16x32_bf16 v[52:55], v[178:181], v[246:249], v[52:55]
	s_add_i32 m0, s12, 0x3000
	s_add_u32 s10, s10, s16
	s_addc_u32 s11, s11, 0
	v_mfma_f32_16x16x32_bf16 v[56:59], v[182:185], v[246:249], v[56:59]
	global_load_lds_dwordx4 v254, s[10:11]
	s_add_u32 s98, s98, 0x80
	s_addc_u32 s99, s99, 0
	v_mfma_f32_16x16x32_bf16 v[60:63], v[186:189], v[246:249], v[60:63]
	ds_read_b128 v[246:249], v165 offset:6144
	s_branch .Lgk_loop_766

; template <int KW, int VD, bool SEL> ...
;     ...
;         if (tiles) { jn = __ffsll((long long)tiles) - 1; tiles &= tiles - 1; FL_ISSUE(cur ^ 1, jn); }
;         const char* sK = smem + cur * BUFB;
;         const char* sV = smem + cur * BUFB + KB;
;         f32x4 s[2][4];
;         const float mref0 = (mrow[0] < -1e29f) ? 0.f : mrow[0], mref1 = (mrow[1] < -1e29f) ? 0.f : mrow[1];
;         const float ci0 = (SEL && !((((const u64*)(smem + 69632))[fr] >> j) & 1ull)) ? -1e30f : -mref0;
;         const float ci1 = (SEL && !((((const u64*)(smem + 69632))[16 + fr] >> j) & 1ull)) ? -1e30f : -mref1;
;         const f32x4 cinit0 = (f32x4){ci0, ci0, ci0, ci0}, cinit1 = (f32x4){ci1, ci1, ci1, ci1};
; #pragma unroll
;         for (int tt = 0; tt < 4; ++tt) {
;             const int kr = 32 * (tt >> 1) + (fr >> 2) * 8 + (tt & 1) * 4 + (fr & 3);
;             const bf16x8 kf0 = *(const bf16x8*)(sK + kr * KROWB + (((kcol >> 3) + fq) ^ kswz) * 16);
;             const bf16x8 kf1 = *(const bf16x8*)(sK + kr * KROWB + (((kcol >> 3) + 4 + fq) ^ kswz) * 16);
.LBB0_824:
	v_add_u32_e32 v100, s26, v179
	v_add_u32_e32 v185, v100, v175
	ds_read_b128 v[80:83], v185
	ds_read_b128 v[92:95], v185 offset:1024
	v_cmp_ngt_f32_e32 vcc, s13, v182
	v_add_u32_e32 v194, v100, v176
	ds_read_b128 v[100:103], v194
	ds_read_b128 v[186:189], v194 offset:1024
	s_cmp_lt_i32 s25, 0
	s_cbranch_scc1 .Lfh_diff_nodma
	v_readfirstlane_b32 s27, v174
	s_mul_i32 s28, s25, 0x44000
	s_add_u32 s28, s20, s28
	s_addc_u32 s29, s21, 0
	s_add_u32 s28, s28, s0
	s_addc_u32 s29, s29, s1
	s_lshl_b32 s11, s25, 7
	s_add_u32 s8, s22, s11
	s_addc_u32 s9, s23, 0
	s_xor_b32 s11, s26, 0x8000
	s_add_i32 s11, s11, s27
	s_mov_b32 m0, s11
	s_nop 0
	global_load_lds_dwordx4 v246, s[28:29]
	s_add_i32 m0, s11, 0x1000
	s_nop 0
	global_load_lds_dwordx4 v247, s[28:29]
	s_add_i32 m0, s11, 0x2000
	s_nop 0
	global_load_lds_dwordx4 v248, s[28:29]
	s_add_i32 m0, s11, 0x3000
	s_nop 0
	global_load_lds_dwordx4 v249, s[28:29]
	s_add_i32 m0, s11, 0x4000
	s_nop 0
	global_load_lds_dwordx4 v250, s[8:9]
	s_add_i32 m0, s11, 0x5000
	s_nop 0
	global_load_lds_dwordx4 v251, s[8:9]
	s_add_i32 m0, s11, 0x6000
	s_nop 0
	global_load_lds_dwordx4 v252, s[8:9]
	s_add_i32 m0, s11, 0x7000
	s_nop 0
	global_load_lds_dwordx4 v253, s[8:9]

; template <int KW, int VD, bool SEL> ...
;     ...
;         const bool pm = (j * 64 + 63 > tmin) || (j * 64 <= lomax);
;         bf16x8 pf[2][2];
; #pragma unroll
;         for (int qt = 0; qt < 2; ++qt) {
;             if (pm) {
;                 const bool selok = SEL ? (((((const u64*)(smem + 69632))[qt * 16 + fr] >> j) & 1ull) != 0) : true;
;                 const int t = tpos[qt], lw = lo[qt];
; #pragma unroll
;                 for (int tt = 0; tt < 4; ++tt)
; #pragma unroll
;                     for (int jj = 0; jj < 4; ++jj) {
;                         const int kp = j * 64 + 32 * (tt >> 1) + fq * 8 + (tt & 1) * 4 + jj;
;                         const bool ok = selok && (kp <= t) && (kp > lw);
;                         s[qt][tt][jj] = ok ? s[qt][tt][jj] : -1e30f;
;                     }
;             }
;             float mx = fmaxf(fmaxf(s[qt][0][0], s[qt][0][1]), fmaxf(s[qt][0][2], s[qt][0][3]));
; #pragma unroll
;             for (int tt = 1; tt < 4; ++tt) mx = fmaxf(mx, fmaxf(fmaxf(s[qt][tt][0], s[qt][tt][1]), fmaxf(s[qt][tt][2], s[qt][tt][3])));
;             const float mref = qt ? mref1 : mref0;
;             if (__builtin_amdgcn_ballot_w64(mx > (mrow[qt] - mref) + 8.0f) != 0ull) {
;                 mx = fmaxf(mx, __shfl_xor(mx, 16));
;                 mx = fmaxf(mx, __shfl_xor(mx, 32));
;                 const float mnew = fmaxf(mrow[qt], mx + mref);
;                 const float alpha = __builtin_amdgcn_exp2f(mrow[qt] - mnew);
;                 const float delta = ((mnew < -1e29f) ? 0.f : mnew) - mref;
;                 lrow[qt] *= alpha;
;                 mrow[qt] = mnew;
; #pragma unroll
;                 for (int dt = 0; dt < VD / 16; ++dt) O[qt][dt] = O[qt][dt] * alpha;
; #pragma unroll
;                 for (int tt = 0; tt < 4; ++tt)
; #pragma unroll
;                     for (int jj = 0; jj < 4; ++jj) s[qt][tt][jj] -= delta;
;             }
.LBB0_826:
	s_andn2_b64 vcc, exec, s[10:11]
	s_cbranch_vccnz .LBB0_828
	v_or_b32_e32 v198, s27, v177
	v_or_b32_e32 v197, 2, v198
	v_or_b32_e32 v196, 3, v198
	v_or_b32_e32 v195, 4, v198
	v_or_b32_e32 v194, 5, v198
	v_or_b32_e32 v193, 6, v198
	v_or_b32_e32 v192, 7, v198
	v_or_b32_e32 v191, 32, v198
	v_or_b32_e32 v190, 34, v198
	v_or_b32_e32 v189, 35, v198
	v_or_b32_e32 v188, 36, v198
	v_or_b32_e32 v187, 37, v198
	v_or_b32_e32 v186, 38, v198
	v_or_b32_e32 v185, 39, v198
	v_cmp_le_u32_e32 vcc, v198, v127
	s_nop 1
	v_cndmask_b32_e32 v108, v121, v108, vcc
	v_cmp_lt_u32_e32 vcc, v198, v127
	s_nop 1
	v_cndmask_b32_e32 v109, v121, v109, vcc
	v_cmp_le_u32_e32 vcc, v197, v127
	s_nop 1
	v_cndmask_b32_e32 v110, v121, v110, vcc
	v_cmp_le_u32_e32 vcc, v196, v127
	s_nop 1
	v_cndmask_b32_e32 v111, v121, v111, vcc
	v_cmp_le_u32_e32 vcc, v195, v127
	s_nop 1
	v_cndmask_b32_e32 v104, v121, v104, vcc
	v_cmp_le_u32_e32 vcc, v194, v127
	s_nop 1
	v_cndmask_b32_e32 v105, v121, v105, vcc
	v_cmp_le_u32_e32 vcc, v193, v127
	s_nop 1
	v_cndmask_b32_e32 v106, v121, v106, vcc
	v_cmp_le_u32_e32 vcc, v192, v127
	s_nop 1
	v_cndmask_b32_e32 v107, v121, v107, vcc
	v_cmp_le_u32_e32 vcc, v191, v127
	s_nop 1
	v_cndmask_b32_e32 v92, v121, v92, vcc
	v_cmp_lt_u32_e32 vcc, v191, v127
	s_nop 1
	v_cndmask_b32_e32 v93, v121, v93, vcc
	v_cmp_le_u32_e32 vcc, v190, v127
	s_nop 1
	v_cndmask_b32_e32 v94, v121, v94, vcc
	v_cmp_le_u32_e32 vcc, v189, v127
	s_nop 1
	v_cndmask_b32_e32 v95, v121, v95, vcc
	v_cmp_le_u32_e32 vcc, v188, v127
	s_nop 1
	v_cndmask_b32_e32 v88, v121, v88, vcc
	v_cmp_le_u32_e32 vcc, v187, v127
	s_nop 1
	v_cndmask_b32_e32 v89, v121, v89, vcc
	v_cmp_le_u32_e32 vcc, v186, v127
	s_nop 1
	v_cndmask_b32_e32 v90, v121, v90, vcc
	v_cmp_le_u32_e32 vcc, v185, v127
	s_nop 1
	v_cndmask_b32_e32 v91, v121, v91, vcc
.LBB0_828:
	v_max3_f32 v200, v108, v109, v110
	v_max3_f32 v201, v111, v104, v105
	v_max3_f32 v200, v200, v106, v107
	v_max3_f32 v201, v201, v92, v93
	v_max3_f32 v200, v200, v94, v95
	v_max3_f32 v201, v201, v88, v89
	v_max3_f32 v200, v200, v90, v91
	v_max_f32_e32 v200, v200, v201
	v_sub_f32_e32 v201, v182, v199
	v_add_f32_e32 v201, 0x41000000, v201
	v_cmp_gt_f32_e32 vcc, v200, v201
	s_cbranch_vccz .LBB0_830
	ds_bpermute_b32 v201, v163, v200
	v_max_f32_e32 v200, v200, v200
	v_max_f32_e32 v202, v182, v182
	s_waitcnt lgkmcnt(0)
	v_max_f32_e32 v201, v201, v201
	v_max_f32_e32 v200, v200, v201
	ds_bpermute_b32 v201, v162, v200
	s_waitcnt lgkmcnt(0)
	v_max_f32_e32 v201, v201, v201
	v_max_f32_e32 v200, v200, v201
	v_add_f32_e32 v200, v199, v200
	v_max_f32_e32 v200, v202, v200
	v_sub_f32_e32 v182, v182, v200
	v_exp_f32_e32 v182, v182
	v_cmp_ngt_f32_e32 vcc, s13, v200
	v_mul_f32_e32 v145, v145, v182
	s_nop 0
	v_cndmask_b32_e32 v201, 0, v200, vcc
	v_pk_mul_f32 v[62:63], v[62:63], v[182:183] op_sel_hi:[1,0]
	v_pk_mul_f32 v[60:61], v[60:61], v[182:183] op_sel_hi:[1,0]
	v_pk_mul_f32 v[58:59], v[58:59], v[182:183] op_sel_hi:[1,0]
	v_pk_mul_f32 v[56:57], v[56:57], v[182:183] op_sel_hi:[1,0]
	v_pk_mul_f32 v[54:55], v[54:55], v[182:183] op_sel_hi:[1,0]
	v_pk_mul_f32 v[52:53], v[52:53], v[182:183] op_sel_hi:[1,0]
	v_pk_mul_f32 v[50:51], v[50:51], v[182:183] op_sel_hi:[1,0]
	v_pk_mul_f32 v[48:49], v[48:49], v[182:183] op_sel_hi:[1,0]
	v_pk_mul_f32 v[46:47], v[46:47], v[182:183] op_sel_hi:[1,0]
	v_pk_mul_f32 v[44:45], v[44:45], v[182:183] op_sel_hi:[1,0]
	v_pk_mul_f32 v[42:43], v[42:43], v[182:183] op_sel_hi:[1,0]
	v_pk_mul_f32 v[40:41], v[40:41], v[182:183] op_sel_hi:[1,0]
	v_pk_mul_f32 v[38:39], v[38:39], v[182:183] op_sel_hi:[1,0]
	v_pk_mul_f32 v[36:37], v[36:37], v[182:183] op_sel_hi:[1,0]
	v_pk_mul_f32 v[34:35], v[34:35], v[182:183] op_sel_hi:[1,0]
	v_pk_mul_f32 v[32:33], v[32:33], v[182:183] op_sel_hi:[1,0]
	v_sub_f32_e32 v182, v201, v199
	v_pk_add_f32 v[108:109], v[108:109], v[182:183] op_sel_hi:[1,0] neg_lo:[0,1] neg_hi:[0,1]
	v_pk_add_f32 v[110:111], v[110:111], v[182:183] op_sel_hi:[1,0] neg_lo:[0,1] neg_hi:[0,1]
	v_pk_add_f32 v[104:105], v[104:105], v[182:183] op_sel_hi:[1,0] neg_lo:[0,1] neg_hi:[0,1]
	v_pk_add_f32 v[106:107], v[106:107], v[182:183] op_sel_hi:[1,0] neg_lo:[0,1] neg_hi:[0,1]
	v_pk_add_f32 v[92:93], v[92:93], v[182:183] op_sel_hi:[1,0] neg_lo:[0,1] neg_hi:[0,1]
	v_pk_add_f32 v[94:95], v[94:95], v[182:183] op_sel_hi:[1,0] neg_lo:[0,1] neg_hi:[0,1]
	v_pk_add_f32 v[88:89], v[88:89], v[182:183] op_sel_hi:[1,0] neg_lo:[0,1] neg_hi:[0,1]
	v_pk_add_f32 v[90:91], v[90:91], v[182:183] op_sel_hi:[1,0] neg_lo:[0,1] neg_hi:[0,1]
	v_mov_b32_e32 v182, v200

; __device__ __forceinline__ f32x4 mfma16(bf16x8 a, bf16x8 b, f32x4 c) { return __builtin_amdgcn_mfma_f32_16x16x32_bf16(a, b, c, 0, 0, 0); }
; template <class Epi>
; __device__ __forceinline__ void gemm_tile(const bf16_t* __restrict__ A, const bf16_t* __restrict__ Bt, int K, int row0, int col0, const Epi& epi, char* smem,
;                                           bool prefetched, bool nvalid, int nrow0, int ncol0) {
;     ...
;     for (int kt = 0; kt < nk; ++kt) {
;         const int cur = kt & 1;
;         if (kt + 1 < nk) GLDS_STAGE(cur ^ 1, pA, pB, kt + 1);
;         const char* cb = smem + cur * 2 * TILE_B;
; #pragma unroll
;         for (int ks = 0; ks < 2; ++ks) {
;             bf16x8 a[4], b[4];
; #pragma unroll
;             for (int m = 0; m < 4; ++m) a[m] = *(const bf16x8*)(cb + offA[m][ks]);
; #pragma unroll
;             for (int n = 0; n < 4; ++n) b[n] = *(const bf16x8*)(cb + offB[n][ks]);
; #pragma unroll
;             for (int m = 0; m < 4; ++m)
; #pragma unroll
;                 for (int n = 0; n < 4; ++n) acc[m][n] = mfma16(b[n], a[m], acc[m][n]);
;         }
;         asm volatile("s_waitcnt vmcnt(0)" ::: "memory");
;         __syncthreads();
.Lgk_loop_895:
	s_and_b32 s3, s1, 0x8000
	s_xor_b32 s10, s3, 0x8000
	v_or_b32_e32 v131, s3, v111
	v_add_u32_e32 v144, s3, v109
	s_add_i32 m0, s11, 0x4000
	s_nop 0
	s_waitcnt lgkmcnt(6)
	v_mfma_f32_16x16x32_bf16 v[0:3], v[92:95], v[174:177], v[0:3]
	global_load_lds_dwordx4 v255, s[100:101]
	ds_read_b128 v[132:135], v131 offset:16384
	s_waitcnt lgkmcnt(6)
	v_mfma_f32_16x16x32_bf16 v[4:7], v[96:99], v[174:177], v[4:7]
	ds_read_b128 v[136:139], v131 offset:16896
	s_add_i32 m0, s11, 0x5000
	s_add_u32 s8, s100, s13
	s_addc_u32 s9, s101, 0
	s_waitcnt lgkmcnt(6)
	v_mfma_f32_16x16x32_bf16 v[8:11], v[100:103], v[174:177], v[8:11]
	global_load_lds_dwordx4 v255, s[8:9]
	ds_read_b128 v[140:143], v131 offset:20480
	s_waitcnt lgkmcnt(6)
	v_mfma_f32_16x16x32_bf16 v[12:15], v[104:107], v[174:177], v[12:15]
	ds_read_b128 v[170:173], v131 offset:20992
	ds_read_b128 v[174:177], v144
	s_add_i32 m0, s11, 0x6000
	s_add_u32 s8, s8, s13
	s_addc_u32 s9, s9, 0
	s_waitcnt lgkmcnt(7)
	v_mfma_f32_16x16x32_bf16 v[16:19], v[92:95], v[178:181], v[16:19]
	global_load_lds_dwordx4 v255, s[8:9]
	v_mfma_f32_16x16x32_bf16 v[20:23], v[96:99], v[178:181], v[20:23]
	s_add_i32 m0, s11, 0x7000
	s_add_u32 s8, s8, s13
	s_addc_u32 s9, s9, 0
	v_mfma_f32_16x16x32_bf16 v[24:27], v[100:103], v[178:181], v[24:27]
	global_load_lds_dwordx4 v255, s[8:9]
	s_add_u32 s100, s100, 0x80
	s_addc_u32 s101, s101, 0
	v_mfma_f32_16x16x32_bf16 v[28:31], v[104:107], v[178:181], v[28:31]
	ds_read_b128 v[178:181], v144 offset:2048
	s_waitcnt lgkmcnt(7)
	v_mfma_f32_16x16x32_bf16 v[32:35], v[92:95], v[246:249], v[32:35]
	v_mfma_f32_16x16x32_bf16 v[36:39], v[96:99], v[246:249], v[36:39]
	v_mfma_f32_16x16x32_bf16 v[40:43], v[100:103], v[246:249], v[40:43]
	v_mfma_f32_16x16x32_bf16 v[44:47], v[104:107], v[246:249], v[44:47]
	ds_read_b128 v[246:249], v144 offset:4096
	s_waitcnt lgkmcnt(7)
	v_mfma_f32_16x16x32_bf16 v[48:51], v[92:95], v[250:253], v[48:51]
	v_mfma_f32_16x16x32_bf16 v[52:55], v[96:99], v[250:253], v[52:55]
	v_mfma_f32_16x16x32_bf16 v[56:59], v[100:103], v[250:253], v[56:59]
	v_mfma_f32_16x16x32_bf16 v[60:63], v[104:107], v[250:253], v[60:63]
	ds_read_b128 v[250:253], v144 offset:6144
	s_waitcnt lgkmcnt(3)
	v_mfma_f32_16x16x32_bf16 v[0:3], v[132:135], v[174:177], v[0:3]
	v_mfma_f32_16x16x32_bf16 v[4:7], v[136:139], v[174:177], v[4:7]
	v_mfma_f32_16x16x32_bf16 v[8:11], v[140:143], v[174:177], v[8:11]
	v_mfma_f32_16x16x32_bf16 v[12:15], v[170:173], v[174:177], v[12:15]
	s_waitcnt lgkmcnt(2)
	v_mfma_f32_16x16x32_bf16 v[16:19], v[132:135], v[178:181], v[16:19]
	v_mfma_f32_16x16x32_bf16 v[20:23], v[136:139], v[178:181], v[20:23]
	v_mfma_f32_16x16x32_bf16 v[24:27], v[140:143], v[178:181], v[24:27]
	v_mfma_f32_16x16x32_bf16 v[28:31], v[170:173], v[178:181], v[28:31]
	s_waitcnt vmcnt(0)
	s_waitcnt lgkmcnt(0)
	s_barrier
	s_add_i32 s1, s1, 0x8000
	s_cmp_eq_u32 s1, 0x78000
	s_cbranch_scc1 .Lgk_tail_895
	v_or_b32_e32 v131, s10, v110
	v_add_u32_e32 v144, s10, v108
	s_add_i32 s11, s3, s12
	ds_read_b128 v[174:177], v144
	ds_read_b128 v[92:95], v131 offset:16384
	s_mov_b32 m0, s11
	s_nop 0
	v_mfma_f32_16x16x32_bf16 v[32:35], v[132:135], v[246:249], v[32:35]
	global_load_lds_dwordx4 v254, s[98:99]
	ds_read_b128 v[96:99], v131 offset:16896
	v_mfma_f32_16x16x32_bf16 v[36:39], v[136:139], v[246:249], v[36:39]
	ds_read_b128 v[100:103], v131 offset:20480
	s_add_i32 m0, s11, 0x1000
	s_add_u32 s8, s98, s13
	s_addc_u32 s9, s99, 0
	v_mfma_f32_16x16x32_bf16 v[40:43], v[140:143], v[246:249], v[40:43]
	global_load_lds_dwordx4 v254, s[8:9]
	ds_read_b128 v[104:107], v131 offset:20992
	v_mfma_f32_16x16x32_bf16 v[44:47], v[170:173], v[246:249], v[44:47]
	ds_read_b128 v[178:181], v144 offset:2048
	ds_read_b128 v[246:249], v144 offset:4096
	s_add_i32 m0, s11, 0x2000
	s_add_u32 s8, s8, s13
	s_addc_u32 s9, s9, 0
	v_mfma_f32_16x16x32_bf16 v[48:51], v[132:135], v[250:253], v[48:51]
	global_load_lds_dwordx4 v254, s[8:9]
	v_mfma_f32_16x16x32_bf16 v[52:55], v[136:139], v[250:253], v[52:55]
	s_add_i32 m0, s11, 0x3000
	s_add_u32 s8, s8, s13
	s_addc_u32 s9, s9, 0
	v_mfma_f32_16x16x32_bf16 v[56:59], v[140:143], v[250:253], v[56:59]
	global_load_lds_dwordx4 v254, s[8:9]
	s_add_u32 s98, s98, 0x80
	s_addc_u32 s99, s99, 0
	v_mfma_f32_16x16x32_bf16 v[60:63], v[170:173], v[250:253], v[60:63]
	ds_read_b128 v[250:253], v144 offset:6144
	s_branch .Lgk_loop_895

; __device__ __forceinline__ u32x2 pack4(f32x4 v) { u32x2 r; r.x = cvt_pk_bf16(v[0], v[1]); r.y = cvt_pk_bf16(v[2], v[3]); return r; }
; __device__ __forceinline__ void rmsnorm_phase(const float* x, const float* g, bf16_t* outb, float* outf) {
;     ...
;     for (int row = gw; row < T; row += nw) {
;         const float* xr = x + (size_t)row * D;
;         f32x4 v[4];
;         float ss = 0.f;
; #pragma unroll
;         for (int i = 0; i < 4; ++i) { v[i] = __builtin_nontemporal_load((const f32x4*)(xr + (lane + i * 64) * 4)); ss += v[i][0] * v[i][0] + v[i][1] * v[i][1] + v[i][2] * v[i][2] + v[i][3] * v[i][3]; }
; #pragma unroll
;         for (int o = 32; o >= 1; o >>= 1) ss += __shfl_xor(ss, o);
;         const float r = rsqrtf(ss * (1.0f / D) + EPS);
; #pragma unroll
;         for (int i = 0; i < 4; ++i) {
;             const f32x4 y = v[i] * r * gv[i];
;             if (outb) *(u32x2*)(outb + (size_t)row * D + (lane + i * 64) * 4) = pack4(y);
;             else __builtin_nontemporal_store(y, (f32x4*)(outf + (size_t)row * D + (lane + i * 64) * 4));
;         }
;     }
.LBB0_945:
	global_load_dwordx4 v[22:25], v[18:19], off offset:-3072 nt
	global_load_dwordx4 v[26:29], v[18:19], off offset:-2048 nt
	global_load_dwordx4 v[30:33], v[18:19], off offset:-1024 nt
	global_load_dwordx4 v[34:37], v[18:19], off nt
	v_add_u32_e32 v21, s40, v21
	v_cmp_lt_i32_e32 vcc, s11, v21
	s_or_b64 s[8:9], vcc, s[8:9]
	v_lshl_add_u64 v[18:19], v[18:19], 0, s[6:7]
	s_waitcnt vmcnt(0)
	v_mov_b32_e32 v40, v23
	v_mov_b32_e32 v41, v27
	v_mov_b32_e32 v38, v22
	v_mov_b32_e32 v39, v26
	v_mov_b32_e32 v48, v31
	v_mov_b32_e32 v49, v35
	v_pk_mul_f32 v[40:41], v[40:41], v[40:41]
	v_mov_b32_e32 v42, v24
	v_mov_b32_e32 v43, v28
	v_mov_b32_e32 v46, v30
	v_mov_b32_e32 v47, v34
	v_pk_mul_f32 v[48:49], v[48:49], v[48:49]
	v_pk_fma_f32 v[38:39], v[38:39], v[38:39], v[40:41]
	v_mov_b32_e32 v44, v25
	v_mov_b32_e32 v45, v29
	v_mov_b32_e32 v50, v32
	v_mov_b32_e32 v51, v36
	v_pk_fma_f32 v[40:41], v[46:47], v[46:47], v[48:49]
	v_pk_fma_f32 v[38:39], v[42:43], v[42:43], v[38:39]
	v_mov_b32_e32 v52, v33
	v_mov_b32_e32 v53, v37
	v_pk_fma_f32 v[40:41], v[50:51], v[50:51], v[40:41]
	v_pk_fma_f32 v[38:39], v[44:45], v[44:45], v[38:39]
	v_pk_fma_f32 v[40:41], v[52:53], v[52:53], v[40:41]
	v_add_f32_e32 v38, v38, v39
	v_add_f32_e32 v38, v38, v40
	v_add_f32_e32 v38, v38, v41
	v_mov_b32_e32 v39, v38
	s_nop 1
	v_permlane32_swap_b32_e32 v38, v39
	v_add_f32_e32 v38, v38, v39
	v_mov_b32_e32 v39, v38
	s_nop 1
	v_permlane16_swap_b32_e32 v38, v39
	v_add_f32_e32 v38, v38, v39
	s_nop 1
	v_add_f32_dpp v38, v38, v38 row_ror:8 row_mask:0xf bank_mask:0xf
	s_nop 1
	v_add_f32_dpp v38, v38, v38 row_ror:4 row_mask:0xf bank_mask:0xf
	s_nop 1
	v_add_f32_dpp v38, v38, v38 quad_perm:[2,3,0,1] row_mask:0xf bank_mask:0xf
	s_nop 1
	v_add_f32_dpp v38, v38, v38 quad_perm:[1,0,3,2] row_mask:0xf bank_mask:0xf
	v_fmamk_f32 v38, v38, 0x3a800000, v20
	v_mul_f32_e32 v39, 0x4b800000, v38
	v_cmp_gt_f32_e32 vcc, s10, v38
	s_nop 1
	v_cndmask_b32_e32 v38, v38, v39, vcc
	v_rsq_f32_e32 v38, v38
	s_nop 0
	v_mul_f32_e32 v39, 0x45800000, v38
	v_cndmask_b32_e32 v38, v38, v39, vcc
	v_pk_mul_f32 v[22:23], v[22:23], v[38:39] op_sel_hi:[1,0]
	v_pk_mul_f32 v[24:25], v[24:25], v[38:39] op_sel_hi:[1,0]
	v_pk_mul_f32 v[26:27], v[26:27], v[38:39] op_sel_hi:[1,0]
	v_pk_mul_f32 v[28:29], v[28:29], v[38:39] op_sel_hi:[1,0]
	v_pk_mul_f32 v[30:31], v[30:31], v[38:39] op_sel_hi:[1,0]
	v_pk_mul_f32 v[32:33], v[32:33], v[38:39] op_sel_hi:[1,0]
	v_pk_mul_f32 v[34:35], v[34:35], v[38:39] op_sel_hi:[1,0]
	v_pk_mul_f32 v[36:37], v[36:37], v[38:39] op_sel_hi:[1,0]
	v_pk_mul_f32 v[24:25], v[10:11], v[24:25]
	v_pk_mul_f32 v[22:23], v[8:9], v[22:23]
	v_pk_mul_f32 v[28:29], v[2:3], v[28:29]
	v_pk_mul_f32 v[26:27], v[0:1], v[26:27]
	v_pk_mul_f32 v[32:33], v[6:7], v[32:33]
	v_pk_mul_f32 v[30:31], v[4:5], v[30:31]
	v_pk_mul_f32 v[36:37], v[14:15], v[36:37]
	v_pk_mul_f32 v[34:35], v[12:13], v[34:35]
	v_cvt_pk_bf16_f32 v22, v22, v23
	v_cvt_pk_bf16_f32 v23, v24, v25
	v_cvt_pk_bf16_f32 v24, v26, v27
	v_cvt_pk_bf16_f32 v25, v28, v29
	v_cvt_pk_bf16_f32 v26, v30, v31
	v_cvt_pk_bf16_f32 v27, v32, v33
	v_cvt_pk_bf16_f32 v28, v34, v35
	v_cvt_pk_bf16_f32 v29, v36, v37
	global_store_dwordx2 v[16:17], v[22:23], off
	global_store_dwordx2 v[16:17], v[24:25], off offset:512
	global_store_dwordx2 v[16:17], v[26:27], off offset:1024
	global_store_dwordx2 v[16:17], v[28:29], off offset:1536
	v_lshl_add_u64 v[16:17], v[16:17], 0, s[2:3]
	s_andn2_b64 exec, exec, s[8:9]
	s_cbranch_execnz .LBB0_945

; __device__ __forceinline__ f32x4 mfma16(bf16x8 a, bf16x8 b, f32x4 c) { return __builtin_amdgcn_mfma_f32_16x16x32_bf16(a, b, c, 0, 0, 0); }
; template <class Epi>
; __device__ __forceinline__ void gemm_tile(const bf16_t* __restrict__ A, const bf16_t* __restrict__ Bt, int K, int row0, int col0, const Epi& epi, char* smem,
;                                           bool prefetched, bool nvalid, int nrow0, int ncol0) {
;     ...
;     for (int kt = 0; kt < nk; ++kt) {
;         const int cur = kt & 1;
;         if (kt + 1 < nk) GLDS_STAGE(cur ^ 1, pA, pB, kt + 1);
;         const char* cb = smem + cur * 2 * TILE_B;
; #pragma unroll
;         for (int ks = 0; ks < 2; ++ks) {
;             bf16x8 a[4], b[4];
; #pragma unroll
;             for (int m = 0; m < 4; ++m) a[m] = *(const bf16x8*)(cb + offA[m][ks]);
; #pragma unroll
;             for (int n = 0; n < 4; ++n) b[n] = *(const bf16x8*)(cb + offB[n][ks]);
; #pragma unroll
;             for (int m = 0; m < 4; ++m)
; #pragma unroll
;                 for (int n = 0; n < 4; ++n) acc[m][n] = mfma16(b[n], a[m], acc[m][n]);
;         }
;         asm volatile("s_waitcnt vmcnt(0)" ::: "memory");
;         __syncthreads();
.LBB0_998:
	v_readfirstlane_b32 s98, v106
	v_readfirstlane_b32 s99, v107
	v_readfirstlane_b32 s10, v108
	v_readfirstlane_b32 s100, v120
	v_readfirstlane_b32 s101, v121
	v_readfirstlane_b32 s17, v149
	s_nop 3
	s_sub_u32 s18, s10, s98
	s_and_b32 s98, s98, 0xffffff80
	s_and_b32 s100, s100, 0xffffff80
	s_nop 1
	v_subrev_u32_e32 v254, s98, v106
	v_subrev_u32_e32 v255, s100, v120
	s_add_i32 s13, s17, 0x8000
	s_mov_b32 m0, s13
	s_nop 0
	global_load_lds_dwordx4 v254, s[98:99]
	s_add_i32 m0, s13, 0x1000
	s_add_u32 s10, s98, s18
	s_addc_u32 s11, s99, 0
	global_load_lds_dwordx4 v254, s[10:11]
	s_add_i32 m0, s13, 0x2000
	s_add_u32 s10, s10, s18
	s_addc_u32 s11, s11, 0
	global_load_lds_dwordx4 v254, s[10:11]
	s_add_i32 m0, s13, 0x3000
	s_add_u32 s10, s10, s18
	s_addc_u32 s11, s11, 0
	global_load_lds_dwordx4 v254, s[10:11]
	s_add_u32 s98, s98, 0x80
	s_addc_u32 s99, s99, 0
	ds_read_b128 v[184:187], v130
	ds_read_b128 v[106:109], v133 offset:16384
	ds_read_b128 v[118:121], v133 offset:16896
	ds_read_b128 v[122:125], v133 offset:20480
	ds_read_b128 v[158:161], v133 offset:20992
	ds_read_b128 v[188:191], v130 offset:2048
	ds_read_b128 v[246:249], v130 offset:4096
	ds_read_b128 v[250:253], v130 offset:6144
.Lgk_loop_998:
	s_and_b32 s9, s8, 0x8000
	s_xor_b32 s12, s9, 0x8000
	v_or_b32_e32 v167, s9, v132
	v_add_u32_e32 v110, s9, v131
	s_add_i32 m0, s13, 0x4000
	s_nop 0
	s_waitcnt lgkmcnt(6)
	v_mfma_f32_16x16x32_bf16 v[0:3], v[106:109], v[184:187], v[0:3]
	global_load_lds_dwordx4 v255, s[100:101]
	ds_read_b128 v[168:171], v167 offset:16384
	s_waitcnt lgkmcnt(6)
	v_mfma_f32_16x16x32_bf16 v[4:7], v[118:121], v[184:187], v[4:7]
	ds_read_b128 v[172:175], v167 offset:16896
	s_add_i32 m0, s13, 0x5000
	s_add_u32 s10, s100, s18
	s_addc_u32 s11, s101, 0
	s_waitcnt lgkmcnt(6)
	v_mfma_f32_16x16x32_bf16 v[8:11], v[122:125], v[184:187], v[8:11]
	global_load_lds_dwordx4 v255, s[10:11]
	ds_read_b128 v[176:179], v167 offset:20480
	s_waitcnt lgkmcnt(6)
	v_mfma_f32_16x16x32_bf16 v[12:15], v[158:161], v[184:187], v[12:15]
	ds_read_b128 v[180:183], v167 offset:20992
	ds_read_b128 v[184:187], v110
	s_add_i32 m0, s13, 0x6000
	s_add_u32 s10, s10, s18
	s_addc_u32 s11, s11, 0
	s_waitcnt lgkmcnt(7)
	v_mfma_f32_16x16x32_bf16 v[16:19], v[106:109], v[188:191], v[16:19]
	global_load_lds_dwordx4 v255, s[10:11]
	v_mfma_f32_16x16x32_bf16 v[20:23], v[118:121], v[188:191], v[20:23]
	s_add_i32 m0, s13, 0x7000
	s_add_u32 s10, s10, s18
	s_addc_u32 s11, s11, 0
	v_mfma_f32_16x16x32_bf16 v[24:27], v[122:125], v[188:191], v[24:27]
	global_load_lds_dwordx4 v255, s[10:11]
	s_add_u32 s100, s100, 0x80
	s_addc_u32 s101, s101, 0
	v_mfma_f32_16x16x32_bf16 v[28:31], v[158:161], v[188:191], v[28:31]
	ds_read_b128 v[188:191], v110 offset:2048
	s_waitcnt lgkmcnt(7)
	v_mfma_f32_16x16x32_bf16 v[32:35], v[106:109], v[246:249], v[32:35]
	v_mfma_f32_16x16x32_bf16 v[36:39], v[118:121], v[246:249], v[36:39]
	v_mfma_f32_16x16x32_bf16 v[40:43], v[122:125], v[246:249], v[40:43]
	v_mfma_f32_16x16x32_bf16 v[44:47], v[158:161], v[246:249], v[44:47]
	ds_read_b128 v[246:249], v110 offset:4096
	s_waitcnt lgkmcnt(7)
	v_mfma_f32_16x16x32_bf16 v[48:51], v[106:109], v[250:253], v[48:51]
	v_mfma_f32_16x16x32_bf16 v[52:55], v[118:121], v[250:253], v[52:55]
	v_mfma_f32_16x16x32_bf16 v[56:59], v[122:125], v[250:253], v[56:59]
	v_mfma_f32_16x16x32_bf16 v[60:63], v[158:161], v[250:253], v[60:63]
	ds_read_b128 v[250:253], v110 offset:6144
	s_waitcnt lgkmcnt(3)
	v_mfma_f32_16x16x32_bf16 v[0:3], v[168:171], v[184:187], v[0:3]
	v_mfma_f32_16x16x32_bf16 v[4:7], v[172:175], v[184:187], v[4:7]
	v_mfma_f32_16x16x32_bf16 v[8:11], v[176:179], v[184:187], v[8:11]
	v_mfma_f32_16x16x32_bf16 v[12:15], v[180:183], v[184:187], v[12:15]
	s_waitcnt lgkmcnt(2)
	v_mfma_f32_16x16x32_bf16 v[16:19], v[168:171], v[188:191], v[16:19]
	v_mfma_f32_16x16x32_bf16 v[20:23], v[172:175], v[188:191], v[20:23]
	v_mfma_f32_16x16x32_bf16 v[24:27], v[176:179], v[188:191], v[24:27]
	v_mfma_f32_16x16x32_bf16 v[28:31], v[180:183], v[188:191], v[28:31]
	s_waitcnt vmcnt(0)
	s_waitcnt lgkmcnt(0)
	s_barrier
	s_add_i32 s8, s8, 0x8000
	s_cmp_eq_u32 s8, 0x78000
	s_cbranch_scc1 .Lgk_tail_998
	v_or_b32_e32 v167, s12, v133
	v_add_u32_e32 v110, s12, v130
	s_add_i32 s13, s9, s17
	ds_read_b128 v[184:187], v110
	ds_read_b128 v[106:109], v167 offset:16384
	s_mov_b32 m0, s13
	s_nop 0
	v_mfma_f32_16x16x32_bf16 v[32:35], v[168:171], v[246:249], v[32:35]
	global_load_lds_dwordx4 v254, s[98:99]
	ds_read_b128 v[118:121], v167 offset:16896
	v_mfma_f32_16x16x32_bf16 v[36:39], v[172:175], v[246:249], v[36:39]
	ds_read_b128 v[122:125], v167 offset:20480
	s_add_i32 m0, s13, 0x1000
	s_add_u32 s10, s98, s18
	s_addc_u32 s11, s99, 0
	v_mfma_f32_16x16x32_bf16 v[40:43], v[176:179], v[246:249], v[40:43]
	global_load_lds_dwordx4 v254, s[10:11]
	ds_read_b128 v[158:161], v167 offset:20992
	v_mfma_f32_16x16x32_bf16 v[44:47], v[180:183], v[246:249], v[44:47]
	ds_read_b128 v[188:191], v110 offset:2048
	ds_read_b128 v[246:249], v110 offset:4096
	s_add_i32 m0, s13, 0x2000
	s_add_u32 s10, s10, s18
	s_addc_u32 s11, s11, 0
	v_mfma_f32_16x16x32_bf16 v[48:51], v[168:171], v[250:253], v[48:51]
	global_load_lds_dwordx4 v254, s[10:11]
	v_mfma_f32_16x16x32_bf16 v[52:55], v[172:175], v[250:253], v[52:55]
	s_add_i32 m0, s13, 0x3000
	s_add_u32 s10, s10, s18
	s_addc_u32 s11, s11, 0
	v_mfma_f32_16x16x32_bf16 v[56:59], v[176:179], v[250:253], v[56:59]
	global_load_lds_dwordx4 v254, s[10:11]
	s_add_u32 s98, s98, 0x80
	s_addc_u32 s99, s99, 0
	v_mfma_f32_16x16x32_bf16 v[60:63], v[180:183], v[250:253], v[60:63]
	ds_read_b128 v[250:253], v110 offset:6144
	s_branch .Lgk_loop_998

; __device__ __forceinline__ f32x4 mfma16(bf16x8 a, bf16x8 b, f32x4 c) { return __builtin_amdgcn_mfma_f32_16x16x32_bf16(a, b, c, 0, 0, 0); }
; template <class Epi>
; __device__ __forceinline__ void gemm_tile(const bf16_t* __restrict__ A, const bf16_t* __restrict__ Bt, int K, int row0, int col0, const Epi& epi, char* smem,
;                                           bool prefetched, bool nvalid, int nrow0, int ncol0) {
;     ...
;     for (int kt = 0; kt < nk; ++kt) {
;         const int cur = kt & 1;
;         if (kt + 1 < nk) GLDS_STAGE(cur ^ 1, pA, pB, kt + 1);
;         const char* cb = smem + cur * 2 * TILE_B;
; #pragma unroll
;         for (int ks = 0; ks < 2; ++ks) {
;             bf16x8 a[4], b[4];
; #pragma unroll
;             for (int m = 0; m < 4; ++m) a[m] = *(const bf16x8*)(cb + offA[m][ks]);
; #pragma unroll
;             for (int n = 0; n < 4; ++n) b[n] = *(const bf16x8*)(cb + offB[n][ks]);
; #pragma unroll
;             for (int m = 0; m < 4; ++m)
; #pragma unroll
;                 for (int n = 0; n < 4; ++n) acc[m][n] = mfma16(b[n], a[m], acc[m][n]);
;         }
;         asm volatile("s_waitcnt vmcnt(0)" ::: "memory");
;         __syncthreads();
.LBB0_1054:
	v_readfirstlane_b32 s98, v92
	v_readfirstlane_b32 s99, v93
	v_readfirstlane_b32 s6, v94
	v_readfirstlane_b32 s100, v100
	v_readfirstlane_b32 s101, v101
	v_readfirstlane_b32 s10, v149
	s_nop 3
	s_sub_u32 s11, s6, s98
	s_and_b32 s98, s98, 0xffffff80
	s_and_b32 s100, s100, 0xffffff80
	s_nop 1
	v_subrev_u32_e32 v254, s98, v92
	v_subrev_u32_e32 v255, s100, v100
	s_add_i32 s9, s10, 0x8000
	s_mov_b32 m0, s9
	s_nop 0
	global_load_lds_dwordx4 v254, s[98:99]
	s_add_i32 m0, s9, 0x1000
	s_add_u32 s6, s98, s11
	s_addc_u32 s7, s99, 0
	global_load_lds_dwordx4 v254, s[6:7]
	s_add_i32 m0, s9, 0x2000
	s_add_u32 s6, s6, s11
	s_addc_u32 s7, s7, 0
	global_load_lds_dwordx4 v254, s[6:7]
	s_add_i32 m0, s9, 0x3000
	s_add_u32 s6, s6, s11
	s_addc_u32 s7, s7, 0
	global_load_lds_dwordx4 v254, s[6:7]
	s_add_u32 s98, s98, 0x80
	s_addc_u32 s99, s99, 0
	ds_read_b128 v[150:153], v108
	ds_read_b128 v[92:95], v110 offset:16384
	ds_read_b128 v[96:99], v110 offset:16896
	ds_read_b128 v[100:103], v110 offset:20480
	ds_read_b128 v[104:107], v110 offset:20992
	ds_read_b128 v[154:157], v108 offset:2048
	ds_read_b128 v[246:249], v108 offset:4096
	ds_read_b128 v[250:253], v108 offset:6144
.Lgk_loop_1054:
	s_and_b32 s3, s1, 0x8000
	s_xor_b32 s8, s3, 0x8000
	v_or_b32_e32 v127, s3, v111
	v_add_u32_e32 v144, s3, v109
	s_add_i32 m0, s9, 0x4000
	s_nop 0
	s_waitcnt lgkmcnt(6)
	v_mfma_f32_16x16x32_bf16 v[0:3], v[92:95], v[150:153], v[0:3]
	global_load_lds_dwordx4 v255, s[100:101]
	ds_read_b128 v[128:131], v127 offset:16384
	s_waitcnt lgkmcnt(6)
	v_mfma_f32_16x16x32_bf16 v[4:7], v[96:99], v[150:153], v[4:7]
	ds_read_b128 v[132:135], v127 offset:16896
	s_add_i32 m0, s9, 0x5000
	s_add_u32 s6, s100, s11
	s_addc_u32 s7, s101, 0
	s_waitcnt lgkmcnt(6)
	v_mfma_f32_16x16x32_bf16 v[8:11], v[100:103], v[150:153], v[8:11]
	global_load_lds_dwordx4 v255, s[6:7]
	ds_read_b128 v[136:139], v127 offset:20480
	s_waitcnt lgkmcnt(6)
	v_mfma_f32_16x16x32_bf16 v[12:15], v[104:107], v[150:153], v[12:15]
	ds_read_b128 v[140:143], v127 offset:20992
	ds_read_b128 v[150:153], v144
	s_add_i32 m0, s9, 0x6000
	s_add_u32 s6, s6, s11
	s_addc_u32 s7, s7, 0
	s_waitcnt lgkmcnt(7)
	v_mfma_f32_16x16x32_bf16 v[16:19], v[92:95], v[154:157], v[16:19]
	global_load_lds_dwordx4 v255, s[6:7]
	v_mfma_f32_16x16x32_bf16 v[20:23], v[96:99], v[154:157], v[20:23]
	s_add_i32 m0, s9, 0x7000
	s_add_u32 s6, s6, s11
	s_addc_u32 s7, s7, 0
	v_mfma_f32_16x16x32_bf16 v[24:27], v[100:103], v[154:157], v[24:27]
	global_load_lds_dwordx4 v255, s[6:7]
	s_add_u32 s100, s100, 0x80
	s_addc_u32 s101, s101, 0
	v_mfma_f32_16x16x32_bf16 v[28:31], v[104:107], v[154:157], v[28:31]
	ds_read_b128 v[154:157], v144 offset:2048
	s_waitcnt lgkmcnt(7)
	v_mfma_f32_16x16x32_bf16 v[32:35], v[92:95], v[246:249], v[32:35]
	v_mfma_f32_16x16x32_bf16 v[36:39], v[96:99], v[246:249], v[36:39]
	v_mfma_f32_16x16x32_bf16 v[40:43], v[100:103], v[246:249], v[40:43]
	v_mfma_f32_16x16x32_bf16 v[44:47], v[104:107], v[246:249], v[44:47]
	ds_read_b128 v[246:249], v144 offset:4096
	s_waitcnt lgkmcnt(7)
	v_mfma_f32_16x16x32_bf16 v[48:51], v[92:95], v[250:253], v[48:51]
	v_mfma_f32_16x16x32_bf16 v[52:55], v[96:99], v[250:253], v[52:55]
	v_mfma_f32_16x16x32_bf16 v[56:59], v[100:103], v[250:253], v[56:59]
	v_mfma_f32_16x16x32_bf16 v[60:63], v[104:107], v[250:253], v[60:63]
	ds_read_b128 v[250:253], v144 offset:6144
	s_waitcnt lgkmcnt(3)
	v_mfma_f32_16x16x32_bf16 v[0:3], v[128:131], v[150:153], v[0:3]
	v_mfma_f32_16x16x32_bf16 v[4:7], v[132:135], v[150:153], v[4:7]
	v_mfma_f32_16x16x32_bf16 v[8:11], v[136:139], v[150:153], v[8:11]
	v_mfma_f32_16x16x32_bf16 v[12:15], v[140:143], v[150:153], v[12:15]
	s_waitcnt lgkmcnt(2)
	v_mfma_f32_16x16x32_bf16 v[16:19], v[128:131], v[154:157], v[16:19]
	v_mfma_f32_16x16x32_bf16 v[20:23], v[132:135], v[154:157], v[20:23]
	v_mfma_f32_16x16x32_bf16 v[24:27], v[136:139], v[154:157], v[24:27]
	v_mfma_f32_16x16x32_bf16 v[28:31], v[140:143], v[154:157], v[28:31]
	s_waitcnt vmcnt(0)
	s_waitcnt lgkmcnt(0)
	s_barrier
	s_add_i32 s1, s1, 0x8000
	s_cmp_eq_u32 s1, 0x1f8000
	s_cbranch_scc1 .Lgk_tail_1054
	v_or_b32_e32 v127, s8, v110
	v_add_u32_e32 v144, s8, v108
	s_add_i32 s9, s3, s10
	ds_read_b128 v[150:153], v144
	ds_read_b128 v[92:95], v127 offset:16384
	s_mov_b32 m0, s9
	s_nop 0
	v_mfma_f32_16x16x32_bf16 v[32:35], v[128:131], v[246:249], v[32:35]
	global_load_lds_dwordx4 v254, s[98:99]
	ds_read_b128 v[96:99], v127 offset:16896
	v_mfma_f32_16x16x32_bf16 v[36:39], v[132:135], v[246:249], v[36:39]
	ds_read_b128 v[100:103], v127 offset:20480
	s_add_i32 m0, s9, 0x1000
	s_add_u32 s6, s98, s11
	s_addc_u32 s7, s99, 0
	v_mfma_f32_16x16x32_bf16 v[40:43], v[136:139], v[246:249], v[40:43]
	global_load_lds_dwordx4 v254, s[6:7]
	ds_read_b128 v[104:107], v127 offset:20992
	v_mfma_f32_16x16x32_bf16 v[44:47], v[140:143], v[246:249], v[44:47]
	ds_read_b128 v[154:157], v144 offset:2048
	ds_read_b128 v[246:249], v144 offset:4096
	s_add_i32 m0, s9, 0x2000
	s_add_u32 s6, s6, s11
	s_addc_u32 s7, s7, 0
	v_mfma_f32_16x16x32_bf16 v[48:51], v[128:131], v[250:253], v[48:51]
	global_load_lds_dwordx4 v254, s[6:7]
	v_mfma_f32_16x16x32_bf16 v[52:55], v[132:135], v[250:253], v[52:55]
	s_add_i32 m0, s9, 0x3000
	s_add_u32 s6, s6, s11
	s_addc_u32 s7, s7, 0
	v_mfma_f32_16x16x32_bf16 v[56:59], v[136:139], v[250:253], v[56:59]
	global_load_lds_dwordx4 v254, s[6:7]
	s_add_u32 s98, s98, 0x80
	s_addc_u32 s99, s99, 0
	v_mfma_f32_16x16x32_bf16 v[60:63], v[140:143], v[250:253], v[60:63]
	ds_read_b128 v[250:253], v144 offset:6144
	s_branch .Lgk_loop_1054

; __device__ __forceinline__ u32x2 pack4(f32x4 v) { u32x2 r; r.x = cvt_pk_bf16(v[0], v[1]); r.y = cvt_pk_bf16(v[2], v[3]); return r; }
; __device__ __forceinline__ void rmsnorm_phase(const float* x, const float* g, bf16_t* outb, float* outf) {
;     ...
;     for (int row = gw; row < T; row += nw) {
;         const float* xr = x + (size_t)row * D;
;         f32x4 v[4];
;         float ss = 0.f;
; #pragma unroll
;         for (int i = 0; i < 4; ++i) { v[i] = __builtin_nontemporal_load((const f32x4*)(xr + (lane + i * 64) * 4)); ss += v[i][0] * v[i][0] + v[i][1] * v[i][1] + v[i][2] * v[i][2] + v[i][3] * v[i][3]; }
; #pragma unroll
;         for (int o = 32; o >= 1; o >>= 1) ss += __shfl_xor(ss, o);
;         const float r = rsqrtf(ss * (1.0f / D) + EPS);
; #pragma unroll
;         for (int i = 0; i < 4; ++i) {
;             const f32x4 y = v[i] * r * gv[i];
;             if (outb) *(u32x2*)(outb + (size_t)row * D + (lane + i * 64) * 4) = pack4(y);
;             else __builtin_nontemporal_store(y, (f32x4*)(outf + (size_t)row * D + (lane + i * 64) * 4));
;         }
;     }
.LBB0_1104:
	global_load_dwordx4 v[20:23], v[16:17], off offset:-3072 nt
	global_load_dwordx4 v[24:27], v[16:17], off offset:-2048 nt
	global_load_dwordx4 v[28:31], v[16:17], off offset:-1024 nt
	global_load_dwordx4 v[32:35], v[16:17], off nt
	v_add_u32_e32 v112, s40, v112
	v_cmp_lt_i32_e64 s[0:1], s7, v112
	s_or_b64 s[4:5], s[0:1], s[4:5]
	s_waitcnt vmcnt(0)
	v_mov_b32_e32 v38, v21
	v_mov_b32_e32 v39, v25
	v_mov_b32_e32 v36, v20
	v_mov_b32_e32 v37, v24
	v_mov_b32_e32 v46, v29
	v_mov_b32_e32 v47, v33
	v_pk_mul_f32 v[38:39], v[38:39], v[38:39]
	v_mov_b32_e32 v40, v22
	v_mov_b32_e32 v41, v26
	v_mov_b32_e32 v44, v28
	v_mov_b32_e32 v45, v32
	v_pk_mul_f32 v[46:47], v[46:47], v[46:47]
	v_pk_fma_f32 v[36:37], v[36:37], v[36:37], v[38:39]
	v_mov_b32_e32 v42, v23
	v_mov_b32_e32 v43, v27
	v_mov_b32_e32 v48, v30
	v_mov_b32_e32 v49, v34
	v_pk_fma_f32 v[38:39], v[44:45], v[44:45], v[46:47]
	v_pk_fma_f32 v[36:37], v[40:41], v[40:41], v[36:37]
	v_mov_b32_e32 v50, v31
	v_mov_b32_e32 v51, v35
	v_pk_fma_f32 v[38:39], v[48:49], v[48:49], v[38:39]
	v_pk_fma_f32 v[36:37], v[42:43], v[42:43], v[36:37]
	v_pk_fma_f32 v[38:39], v[50:51], v[50:51], v[38:39]
	v_add_f32_e32 v19, v36, v37
	v_add_f32_e32 v19, v19, v38
	v_add_f32_e32 v19, v19, v39
	v_mov_b32_e32 v36, v19
	s_nop 1
	v_permlane32_swap_b32_e32 v19, v36
	v_add_f32_e32 v19, v19, v36
	v_mov_b32_e32 v36, v19
	s_nop 1
	v_permlane16_swap_b32_e32 v19, v36
	v_add_f32_e32 v19, v19, v36
	s_nop 1
	v_add_f32_dpp v19, v19, v19 row_ror:8 row_mask:0xf bank_mask:0xf
	s_nop 1
	v_add_f32_dpp v19, v19, v19 row_ror:4 row_mask:0xf bank_mask:0xf
	s_nop 1
	v_add_f32_dpp v19, v19, v19 quad_perm:[2,3,0,1] row_mask:0xf bank_mask:0xf
	s_nop 1
	v_add_f32_dpp v19, v19, v19 quad_perm:[1,0,3,2] row_mask:0xf bank_mask:0xf
	v_fmamk_f32 v19, v19, 0x3a800000, v18
	v_mul_f32_e32 v36, 0x4b800000, v19
	v_cmp_gt_f32_e32 vcc, s6, v19
	s_nop 1
	v_cndmask_b32_e32 v19, v19, v36, vcc
	v_rsq_f32_e32 v19, v19
	s_nop 0
	v_mul_f32_e32 v36, 0x45800000, v19
	v_cndmask_b32_e32 v36, v19, v36, vcc
	v_pk_mul_f32 v[20:21], v[20:21], v[36:37] op_sel_hi:[1,0]
	v_pk_mul_f32 v[22:23], v[22:23], v[36:37] op_sel_hi:[1,0]
	v_pk_mul_f32 v[24:25], v[24:25], v[36:37] op_sel_hi:[1,0]
	v_pk_mul_f32 v[26:27], v[26:27], v[36:37] op_sel_hi:[1,0]
	v_pk_mul_f32 v[28:29], v[28:29], v[36:37] op_sel_hi:[1,0]
	v_pk_mul_f32 v[30:31], v[30:31], v[36:37] op_sel_hi:[1,0]
	v_pk_mul_f32 v[32:33], v[32:33], v[36:37] op_sel_hi:[1,0]
	v_pk_mul_f32 v[34:35], v[34:35], v[36:37] op_sel_hi:[1,0]
	v_pk_mul_f32 v[22:23], v[2:3], v[22:23]
	v_pk_mul_f32 v[20:21], v[0:1], v[20:21]
	v_pk_mul_f32 v[26:27], v[6:7], v[26:27]
	v_pk_mul_f32 v[24:25], v[4:5], v[24:25]
	v_pk_mul_f32 v[30:31], v[10:11], v[30:31]
	v_pk_mul_f32 v[28:29], v[8:9], v[28:29]
	v_pk_mul_f32 v[34:35], v[14:15], v[34:35]
	v_pk_mul_f32 v[32:33], v[12:13], v[32:33]
	global_store_dwordx4 v[16:17], v[20:23], off offset:-3072 nt
	global_store_dwordx4 v[16:17], v[24:27], off offset:-2048 nt
	global_store_dwordx4 v[16:17], v[28:31], off offset:-1024 nt
	global_store_dwordx4 v[16:17], v[32:35], off nt
	v_lshl_add_u64 v[16:17], v[16:17], 0, s[2:3]
	s_andn2_b64 exec, exec, s[4:5]
	s_cbranch_execnz .LBB0_1104
